# attention: + unit epilogue batched (hoisted goa loads, b128 multiplier reads), K-nope LDS image made row-coalesced for the DMA with XOR swizzle (8 cache lines per piece instead of 64), l-sum as add tr
# speedup vs baseline: 1.0140x; 1.0091x over previous
; __device__ __forceinline__ int lane_id() { int l; asm volatile("v_mbcnt_lo_u32_b32 %0, -1, 0\n\tv_mbcnt_hi_u32_b32 %0, -1, %0" : "=v"(l)); return l; }
; #define AT_LAS __attribute__((address_space(3)))
; #define AT_QLOAD(dst, qb_) do { const bf16_t* Qw_ = Q + (rowbase + (qb_) * 256 + wid * 32) * 768 + h * 96; \
;         _Pragma("unroll") for (int d0 = 0; d0 < 6; ++d0) dst[d0] = *(const bf16x8*)(Qw_ + (size_t)r32 * 768 + d0 * 16 + hi * 8); } while (0)
; template <int THRL>
; __device__ __forceinline__ void attn_item(int b, int h, int s, const bf16_t* Q, const bf16_t* KN, const bf16_t* KR, const bf16_t* V, const float* goa  , bf16_t* Y, float* ssqy, AT_LAS char* shm, int wid0) {
;     int tid_ = wid0 * 64 + lane_id(); asm volatile("" : "+v"(tid_));
;     const int tid = tid_, lane = tid & 63, r32 = lane & 31, hi = lane >> 5; const int wid = __builtin_amdgcn_readfirstlane(tid >> 6);
;     const bool late = wid >= 4;
;     const size_t rowbase = (size_t)b * SEQ;
;     const unsigned lds0 = (unsigned)(uintptr_t)shm;
;     AT_LAS float* wsf = (AT_LAS float*)(shm + LDS_WS) + wid * 64;
;     const bf16_t* ksrc = KN + (rowbase + lane) * 512 + h * 64 + wid * 8;
;     const bf16_t* rsrc = KR + (rowbase + lane) * 32 + (wid & 3) * 8;
;     const bf16_t* vsrc = V + (rowbase + 16 * (wid & 3) + (lane >> 2)) * 512 + h * 64 + (wid >> 2) * 32 + (lane & 3) * 8;
;     const unsigned kdst = lds0 + wid * 1024, rdst = lds0 + (8 + (wid & 3)) * 1024, vdst = lds0 + LDS_V + wid * 1024;
;     ...
;     AT_LAS const char* kp0 = shm + hi * 1024 + r32 * 16;
;     AT_LAS const char* vp0 = shm + LDS_V + ((lane >> 4) & 1) * 32 + (lane & 3) * 8 + (4 * hi + ((lane & 15) >> 2)) * 64;
;     const int qrel = wid * 32 + r32, wq = wid >> 1;
;     bf16x8 qr[6];
;     AT_QLOAD(qr, s);
;     { const int NT0 = 4 * s + 4; AT_DMA(0, 0, NT0); AT_DMA(1, 1, NT0); AT_DMA(2, 1, NT0); }
.LBB13_746:
	s_ashr_i32 s0, s13, 1
	v_readlane_b32 s1, v238, 48
	s_add_i32 s1, s0, s1
	v_writelane_b32 v238, s13, 49
	s_ashr_i32 s0, s1, 3
	s_and_b32 s9, s1, 7
	v_readlane_b32 s1, v238, 2
	v_mbcnt_lo_u32_b32 v0, -1, 0
	v_mbcnt_hi_u32_b32 v0, -1, v0
	v_readlane_b32 s6, v238, 44
	v_readlane_b32 s7, v238, 45
	v_add_u32_e32 v12, s1, v0
	s_ashr_i32 s1, s0, 31
	v_readfirstlane_b32 s8, v12
	s_ashr_i32 s10, s8, 6
	s_and_b32 s11, s10, 3
	v_and_b32_e32 v13, 63, v12
	s_lshl_b64 s[0:1], s[0:1], 11
	s_lshl_b32 s4, s11, 4
	v_bfe_u32 v0, v12, 2, 4
	s_waitcnt lgkmcnt(0)
	v_or_b32_e32 v2, s0, v13
	v_mov_b32_e32 v3, s1
	v_or_b32_e32 v0, s4, v0
	v_lshlrev_b64 v[4:5], 10, v[2:3]
	v_lshlrev_b64 v[6:7], 6, v[2:3]
	v_or_b32_e32 v2, s0, v0
	v_lshlrev_b64 v[2:3], 10, v[2:3]
	v_lshl_add_u64 v[2:3], s[6:7], 0, v[2:3]
	s_ashr_i32 s6, s8, 3
	s_lshl_b32 s11, s11, 10
	s_and_b32 s16, s13, 1
	s_lshl_b32 s2, s10, 3
	s_andn2_b32 s6, s6, 31
	s_or_b32 s18, s11, 0x2000
	s_lshl_b32 s11, s10, 5
	s_and_b32 s5, s8, 0x3fffffc0
	s_ashr_i32 s3, s2, 31
	s_ashr_i32 s7, s6, 31
	s_lshl_b32 s17, s10, 10
	s_add_i32 s78, s18, 0
	s_lshl_b32 s12, s16, 8
	s_ashr_i32 s13, s11, 31
	s_add_u32 s19, s0, s11
	s_addc_u32 s20, s1, s13
	s_add_u32 s0, s19, s12
	v_and_b32_e32 v14, 31, v12
	v_lshlrev_b32_e32 v0, 3, v12
	s_addc_u32 s1, s20, 0
	v_and_b32_e32 v16, 24, v0
	v_lshlrev_b32_e32 v0, 1, v12
	v_or_b32_e32 v22, s11, v14
	s_mulk_i32 s1, 0x600
	s_mul_hi_u32 s11, s0, 0x600
	v_bfe_u32 v15, v12, 5, 1
	v_and_b32_e32 v0, 32, v0
	s_add_i32 s11, s11, s1
	s_mulk_i32 s0, 0x600
	v_readlane_b32 s14, v238, 38
	v_add_u32_e32 v19, 0, v0
	v_lshlrev_b32_e32 v20, 2, v15
	v_lshrrev_b32_e32 v0, 2, v12
	s_add_u32 s0, s14, s0
	v_readlane_b32 s15, v238, 39
	v_and_or_b32 v0, v0, 3, v20
	s_addc_u32 s1, s15, s11
	s_mul_i32 s11, s9, 0xc0
	v_lshlrev_b32_e32 v21, 6, v0
	s_add_u32 s0, s0, s11
	v_mul_u32_u24_e32 v0, 0x300, v14
	s_addc_u32 s1, s1, 0
	v_lshlrev_b32_e32 v0, 1, v0
	v_lshl_add_u64 v[8:9], s[0:1], 0, v[0:1]
	v_lshlrev_b32_e32 v10, 4, v15
	v_mov_b32_e32 v11, v1
	v_lshl_add_u64 v[8:9], v[8:9], 0, v[10:11]
	global_load_dwordx4 v[82:85], v[8:9], off
	global_load_dwordx4 v[86:89], v[8:9], off offset:32
	global_load_dwordx4 v[90:93], v[8:9], off offset:64
	global_load_dwordx4 v[94:97], v[8:9], off offset:96
	global_load_dwordx4 v[98:101], v[8:9], off offset:128
	global_load_dwordx4 v[102:105], v[8:9], off offset:160
	s_cmp_gt_i32 s10, 3
	v_readlane_b32 s12, v238, 40
	s_cselect_b64 s[0:1], -1, 0
	s_cmp_lt_i32 s10, 4
	v_readlane_b32 s13, v238, 41
	s_cselect_b64 s[90:91], -1, 0
	s_lshl_b32 s84, s9, 7
	v_lshl_add_u64 v[4:5], s[12:13], 0, v[4:5]
	v_lshl_add_u64 v[4:5], v[4:5], 0, s[84:85]
	s_lshl_b32 s5, s5, 2
	v_lshl_add_u64 v[122:123], s[2:3], 1, v[4:5]
	v_lshrrev_b32_e32 v214, 3, v13
	v_lshl_add_u32 v214, s10, 3, v214
	v_sub_u32_e32 v214, v214, v13
	v_lshlrev_b32_e32 v214, 10, v214
	v_lshrrev_b32_e32 v215, 4, v13
	v_lshl_add_u32 v215, s10, 2, v215
	v_xor_b32_e32 v215, v215, v13
	v_and_b32_e32 v215, 7, v215
	v_subrev_u32_e32 v215, s10, v215
	v_lshl_add_u32 v214, v215, 4, v214
	v_ashrrev_i32_e32 v215, 31, v214
	v_lshl_add_u64 v[122:123], v[122:123], 0, v[214:215]
	v_readlane_b32 s2, v238, 42
	s_add_i32 s5, s5, 0
	v_readlane_b32 s3, v238, 43
	s_add_i32 s52, s5, 0x14000
	s_mov_b32 s5, s85
	v_lshl_add_u64 v[4:5], s[2:3], 0, v[6:7]
	v_lshl_add_u64 v[2:3], v[2:3], 0, s[84:85]
	s_add_i32 s33, s17, 0
	s_mov_b32 s3, m0
	s_mov_b32 m0, s33
	s_nop 0
	global_load_lds_dwordx4 v[122:123], off
	s_mov_b32 m0, s3
	v_lshl_add_u64 v[124:125], v[4:5], 0, s[4:5]
	v_lshl_add_u64 v[2:3], s[6:7], 1, v[2:3]
	v_lshlrev_b32_e32 v4, 1, v16
	v_mov_b32_e32 v5, v1
	s_mov_b32 s3, m0
	s_mov_b32 m0, s78
	s_nop 0
	global_load_lds_dwordx4 v[124:125], off
	s_mov_b32 m0, s3
	v_readlane_b32 s6, v238, 14
	v_lshl_add_u64 v[126:127], v[2:3], 0, v[4:5]
	s_add_i32 s87, s33, 0xc000
	s_mov_b32 s3, m0
	s_mov_b32 m0, s87
	s_nop 0
	global_load_lds_dwordx4 v[126:127], off
	s_mov_b32 m0, s3
	s_mov_b64 s[12:13], 0x10000
	s_add_i32 s4, s17, s6
	v_lshl_add_u64 v[128:129], v[122:123], 0, s[12:13]
	v_writelane_b32 v238, s4, 50
	s_mov_b32 s3, m0
	s_mov_b32 m0, s4
	s_nop 0
	global_load_lds_dwordx4 v[128:129], off
	s_mov_b32 m0, s3
	s_mov_b64 s[4:5], 0x1000
	v_lshl_add_u64 v[130:131], v[124:125], 0, s[4:5]
	s_add_i32 s4, s18, s6
	v_writelane_b32 v238, s4, 51
	s_mov_b32 s3, m0
	s_mov_b32 m0, s4
	s_nop 0
	global_load_lds_dwordx4 v[130:131], off
	s_mov_b32 m0, s3
	v_lshl_add_u64 v[132:133], v[126:127], 0, s[12:13]
	v_readlane_b32 s6, v238, 15
	s_add_i32 s7, s33, 0xe000
	s_mov_b32 s3, m0
	s_mov_b32 m0, s7
	s_nop 0
	global_load_lds_dwordx4 v[132:133], off
	s_mov_b32 m0, s3
	s_mov_b64 s[12:13], 0x20000
	v_writelane_b32 v238, s17, 52
	s_add_i32 s4, s17, s6
	v_lshl_add_u64 v[134:135], v[122:123], 0, s[12:13]
	v_writelane_b32 v238, s4, 53
	s_mov_b32 s3, m0
	s_mov_b32 m0, s4
	s_nop 0
	global_load_lds_dwordx4 v[134:135], off
; #define AT_LAS __attribute__((address_space(3)))
; #define AT_QLOAD(dst, qb_) do { const bf16_t* Qw_ = Q + (rowbase + (qb_) * 256 + wid * 32) * 768 + h * 96; \
;         _Pragma("unroll") for (int d0 = 0; d0 < 6; ++d0) dst[d0] = *(const bf16x8*)(Qw_ + (size_t)r32 * 768 + d0 * 16 + hi * 8); } while (0)
; template <int THRL>
; __device__ __forceinline__ void attn_item(int b, int h, int s, const bf16_t* Q, const bf16_t* KN, const bf16_t* KR, const bf16_t* V, const float* goa  , bf16_t* Y, float* ssqy, AT_LAS char* shm, int wid0) {
;     ...
;     const int tid = tid_, lane = tid & 63, r32 = lane & 31, hi = lane >> 5; const int wid = __builtin_amdgcn_readfirstlane(tid >> 6);
;     const bool late = wid >= 4;
;     const size_t rowbase = (size_t)b * SEQ;
;     const unsigned lds0 = (unsigned)(uintptr_t)shm;
;     AT_LAS float* wsf = (AT_LAS float*)(shm + LDS_WS) + wid * 64;
;     const bf16_t* ksrc = KN + (rowbase + lane) * 512 + h * 64 + wid * 8;
;     const bf16_t* rsrc = KR + (rowbase + lane) * 32 + (wid & 3) * 8;
;     const bf16_t* vsrc = V + (rowbase + 16 * (wid & 3) + (lane >> 2)) * 512 + h * 64 + (wid >> 2) * 32 + (lane & 3) * 8;
;     const unsigned kdst = lds0 + wid * 1024, rdst = lds0 + (8 + (wid & 3)) * 1024, vdst = lds0 + LDS_V + wid * 1024;
;     ...
;     AT_LAS const char* kp0 = shm + hi * 1024 + r32 * 16;
;     AT_LAS const char* vp0 = shm + LDS_V + ((lane >> 4) & 1) * 32 + (lane & 3) * 8 + (4 * hi + ((lane & 15) >> 2)) * 64;
;     const int qrel = wid * 32 + r32, wq = wid >> 1;
;     bf16x8 qr[6];
;     AT_QLOAD(qr, s);
;     { const int NT0 = 4 * s + 4; AT_DMA(0, 0, NT0); AT_DMA(1, 1, NT0); AT_DMA(2, 1, NT0); }
;     ...
;                 if (jb == wq) { const int kb = 64 * jb + 4 * hi;
; #pragma unroll
;                     for (int r = 0; r < 16; ++r) { const int kv = kb + (r & 3) + 8 * (r >> 2); if (kv > qrel) p0[r] = -INFINITY; if (kv + 32 > qrel) p1[r] = -INFINITY; } }
	s_mov_b32 m0, s3
	s_mov_b64 s[4:5], 0x2000
	s_ashr_i32 s2, s8, 7
	v_lshl_add_u64 v[136:137], v[124:125], 0, s[4:5]
	v_writelane_b32 v238, s18, 54
	s_add_i32 s4, s18, s6
	s_mov_b32 s3, m0
	s_mov_b32 m0, s4
	s_nop 0
	global_load_lds_dwordx4 v[136:137], off
	s_mov_b32 m0, s3
	v_writelane_b32 v238, s4, 55
	s_mov_b32 s3, m0
	s_mov_b32 m0, s7
	s_nop 0
	global_load_lds_dwordx4 v[132:133], off
	s_mov_b32 m0, s3
	s_add_u32 s4, s14, s11
	v_writelane_b32 v238, s7, 56
	s_addc_u32 s5, s15, 0
	s_or_b32 s3, s16, 2
	v_writelane_b32 v238, s3, 57
	v_writelane_b32 v238, s16, 58
	s_xor_b32 s3, s16, 7
	s_mulk_i32 s10, 0x1200
	v_writelane_b32 v238, s3, 59
	s_add_i32 s3, s10, 0
	v_lshlrev_b32_e32 v4, 2, v14
	v_lshl_add_u64 v[2:3], s[4:5], 0, v[0:1]
	s_add_i32 s3, s3, 0x14800
	v_add_u32_e32 v193, s52, v4
	v_lshl_add_u64 v[138:139], v[2:3], 0, v[10:11]
	v_bfe_u32 v2, v12, 1, 5
	v_add_u32_e32 v4, s3, v4
	v_mov_b32_e32 v5, s3
	s_movk_i32 s3, 0x90
	v_lshl_or_b32 v6, s2, 6, v20
	v_or_b32_e32 v140, s19, v2
	v_mad_u32_u24 v5, v2, s3, v5
	v_or_b32_e32 v2, 32, v6
	v_lshl_add_u64 v[148:149], v[126:127], 0, s[12:13]
	v_cmp_gt_i32_e64 s[12:13], v2, v22
	v_or_b32_e32 v2, 33, v6
	s_xor_b32 s86, s16, 5
	v_cmp_gt_i32_e64 s[16:17], v2, v22
	v_or_b32_e32 v2, 2, v6
	v_writelane_b32 v238, s19, 60
	v_cmp_gt_i32_e64 s[18:19], v2, v22
	v_or_b32_e32 v2, 34, v6
	v_writelane_b32 v238, s20, 61
	v_mov_b32_e32 v141, s20
	v_cmp_gt_i32_e64 s[20:21], v2, v22
	v_or_b32_e32 v2, 3, v6
	s_lshl_b32 s4, s9, 8
	v_readlane_b32 s10, v238, 46
	v_cmp_gt_i32_e64 s[22:23], v2, v22
	v_or_b32_e32 v2, 35, v6
	v_and_b32_e32 v3, 1, v12
	v_readlane_b32 s11, v238, 47
	s_add_u32 s4, s10, s4
	v_cmp_gt_i32_e64 s[24:25], v2, v22
	v_or_b32_e32 v2, 8, v6
	s_addc_u32 s5, s11, 0
	v_lshlrev_b32_e32 v0, 6, v3
	v_cmp_gt_i32_e64 s[26:27], v2, v22
	v_or_b32_e32 v2, 40, v6
	v_lshl_add_u64 v[142:143], s[4:5], 0, v[0:1]
	v_cmp_eq_u32_e64 s[4:5], 0, v3
	v_cmp_gt_i32_e64 s[28:29], v2, v22
	v_or_b32_e32 v2, 9, v6
	v_writelane_b32 v238, s4, 62
	v_cmp_gt_i32_e64 s[30:31], v2, v22
	v_or_b32_e32 v2, 41, v6
	v_writelane_b32 v238, s5, 63
	v_cmp_gt_i32_e64 s[34:35], v2, v22
	v_or_b32_e32 v2, 10, v6
	s_lshl_b32 s3, s9, 2
	v_readlane_b32 s4, v238, 36
	v_cmp_gt_i32_e64 s[36:37], v2, v22
	v_or_b32_e32 v2, 42, v6
	s_add_u32 s4, s4, s3
	v_readlane_b32 s3, v238, 37
	v_cmp_gt_i32_e64 s[38:39], v2, v22
	v_or_b32_e32 v2, 11, v6
	s_addc_u32 s5, s3, 0
	v_cmp_gt_i32_e64 s[40:41], v2, v22
	v_or_b32_e32 v2, 43, v6
	v_writelane_b32 v237, s4, 0
	v_cmp_gt_i32_e64 s[42:43], v2, v22
	v_or_b32_e32 v2, 16, v6
	v_writelane_b32 v237, s5, 1
	s_mov_b64 s[4:5], 0x30000
	v_cmp_gt_i32_e64 s[44:45], v2, v22
	v_or_b32_e32 v2, 48, v6
	v_lshl_add_u64 v[144:145], v[122:123], 0, s[4:5]
	s_mov_b64 s[4:5], 0x3000
	v_cmp_gt_i32_e64 s[46:47], v2, v22
	v_or_b32_e32 v2, 17, v6
	v_readlane_b32 s3, v238, 34
	v_lshl_add_u64 v[146:147], v[124:125], 0, s[4:5]
	v_cmp_gt_i32_e64 s[48:49], v2, v22
	v_or_b32_e32 v2, 49, v6
	s_add_u32 s4, s3, s84
	v_readlane_b32 s3, v238, 35
	v_add3_u32 v191, v19, v16, v21
	v_cmp_gt_i32_e64 s[50:51], v2, v22
	v_or_b32_e32 v7, 18, v6
	s_addc_u32 s5, s3, 0
	v_lshlrev_b32_e32 v2, 5, v3
	v_mov_b32_e32 v3, v1
	v_or_b32_e32 v16, 1, v20
	v_lshlrev_b32_e32 v17, 10, v15
	v_lshlrev_b32_e32 v18, 4, v14
	v_lshrrev_b32_e32 v252, 3, v14
	v_lshlrev_b32_e32 v252, 10, v252
	v_and_b32_e32 v253, 7, v14
	v_lshl_add_u32 v252, v253, 7, v252
	v_bfe_u32 v253, v14, 1, 1
	v_xor_b32_e32 v253, v253, v15
	v_lshl_add_u32 v252, v253, 4, v252
	v_bfe_u32 v253, v14, 2, 2
	v_lshl_add_u32 v252, v253, 5, v252
	v_xor_b32_e32 v253, 32, v252
	v_xor_b32_e32 v254, 64, v252
	v_xor_b32_e32 v255, 0x60, v252
	v_cmp_gt_u32_e64 s[6:7], 32, v13
	v_cmp_gt_i32_e64 s[10:11], v6, v22
	v_cmp_lt_i32_e64 s[14:15], v6, v22
	v_add_u32_e32 v194, s52, v10
	v_lshl_add_u64 v[150:151], s[4:5], 0, v[2:3]
	v_cmp_gt_i32_e64 s[52:53], v7, v22
	v_or_b32_e32 v2, 50, v6
	v_or_b32_e32 v3, 19, v6
	v_or_b32_e32 v7, 51, v6
	v_or_b32_e32 v8, 24, v6
	v_or_b32_e32 v9, 56, v6
	v_or_b32_e32 v10, 25, v6
	v_or_b32_e32 v11, 57, v6
	v_or_b32_e32 v12, 26, v6
	v_or_b32_e32 v13, 58, v6
	v_or_b32_e32 v14, 27, v6
	v_or_b32_e32 v6, 59, v6
	v_mul_u32_u24_e32 v15, 0x240, v15
	v_mul_u32_u24_e32 v16, 0x90, v16
	v_add3_u32 v190, 0, v17, v18
	v_add_u32_e32 v192, 0xc000, v191
	s_mov_b32 s8, 0
	v_add_u32_e32 v195, v4, v15
	v_add_u32_e32 v196, v4, v16
	v_add_u32_e32 v197, v5, v0
	s_sub_i32 s3, 0, s2
	v_cmp_gt_i32_e64 s[54:55], v2, v22
	v_cmp_gt_i32_e64 s[56:57], v3, v22
	v_cmp_gt_i32_e64 s[58:59], v7, v22
	v_cmp_gt_i32_e64 s[60:61], v8, v22
	v_cmp_gt_i32_e64 s[62:63], v9, v22
	v_cmp_gt_i32_e64 s[64:65], v10, v22
	v_cmp_gt_i32_e64 s[66:67], v11, v22
	v_cmp_gt_i32_e64 s[68:69], v12, v22
	v_cmp_gt_i32_e64 s[70:71], v13, v22
	v_cmp_gt_i32_e64 s[72:73], v14, v22
	v_cmp_gt_i32_e64 s[74:75], v6, v22
	v_writelane_b32 v237, s3, 2
	s_branch .LBB13_748

; #define AT_LAS __attribute__((address_space(3)))
; #define AT_WAIT_BAR(N) asm volatile("s_waitcnt vmcnt(" #N ") lgkmcnt(0)\n\ts_barrier" ::: "memory")
; __device__ __forceinline__ void qkt(f32x16& p0, f32x16& p1, AT_LAS const char* kb, const bf16x8 (&qr)[6], const f32x16& negm) {
;     bf16x8 kf[12];
; #pragma unroll
;     for (int d0 = 0; d0 < 6; ++d0) { kf[2 * d0] = *(AT_LAS const bf16x8*)(kb + d0 * 2048); kf[2 * d0 + 1] = *(AT_LAS const bf16x8*)(kb + d0 * 2048 + 512); }
;     __builtin_amdgcn_sched_barrier(0);
;     p0 = __builtin_amdgcn_mfma_f32_32x32x16_bf16(kf[0], qr[0], negm, 0, 0, 0); p1 = __builtin_amdgcn_mfma_f32_32x32x16_bf16(kf[1], qr[0], negm, 0, 0, 0);
; #pragma unroll
;     for (int d0 = 1; d0 < 6; ++d0) { p0 = __builtin_amdgcn_mfma_f32_32x32x16_bf16(kf[2 * d0], qr[d0], p0, 0, 0, 0); p1 = __builtin_amdgcn_mfma_f32_32x32x16_bf16(kf[2 * d0 + 1], qr[d0], p1, 0, 0, 0); }
;     asm volatile("s_nop 15\n\ts_nop 7" : "+v"(p0), "+v"(p1));
; }
; template <int THRL>
; __device__ __forceinline__ void attn_item(int b, int h, int s, const bf16_t* Q, const bf16_t* KN, const bf16_t* KR, const bf16_t* V, const float* goa  , bf16_t* Y, float* ssqy, AT_LAS char* shm, int wid0) {
;     ...
;         float mhat = 0.f, l_reg = 0.f; f32x16 o[2]; o[0] = f32x16{}; o[1] = f32x16{};
;         f32x16 negm = f32x16{}; asm volatile("" : "+v"(negm));
;         u32x4 pw0 = u32x4{}, pw1 = u32x4{}, pw2 = u32x4{}, pw3 = u32x4{}; bool have = false;
;         f32x16 p0 = f32x16{}, p1 = f32x16{};
;         AT_WAIT_BAR(6);
;         if (!late) qkt(p0, p1, kp0, qr, negm);
.LBB13_748:
	v_mov_b32_e32 v14, v1
	v_mov_b32_e32 v15, v1
	v_mov_b32_e32 v0, v1
	s_waitcnt lgkmcnt(0)
	v_mov_b32_e32 v2, v1
	v_mov_b32_e32 v3, v1
	v_mov_b32_e32 v4, v1
	v_mov_b32_e32 v5, v1
	v_mov_b32_e32 v6, v1
	v_mov_b32_e32 v7, v1
	v_mov_b32_e32 v8, v1
	v_mov_b32_e32 v9, v1
	v_mov_b32_e32 v10, v1
	v_mov_b32_e32 v11, v1
	v_mov_b32_e32 v12, v1
	v_mov_b32_e32 v13, v1
	v_mov_b64_e32 v[80:81], v[14:15]
	v_mov_b64_e32 v[78:79], v[12:13]
	v_mov_b64_e32 v[76:77], v[10:11]
	v_mov_b64_e32 v[74:75], v[8:9]
	v_mov_b64_e32 v[72:73], v[6:7]
	v_mov_b64_e32 v[70:71], v[4:5]
	v_mov_b64_e32 v[68:69], v[2:3]
	v_mov_b64_e32 v[66:67], v[0:1]
	s_waitcnt vmcnt(6) lgkmcnt(0)
	s_barrier
	v_cndmask_b32_e64 v16, 0, 1, s[90:91]
	v_cmp_ne_u32_e64 s[76:77], 1, v16
	s_andn2_b64 vcc, exec, s[90:91]
	s_cbranch_vccnz .LBB13_750
	ds_read_b128 v[2:5], v252
	ds_read_b128 v[6:9], v252 offset:4096
	ds_read_b128 v[10:13], v253
	ds_read_b128 v[14:17], v253 offset:4096
	ds_read_b128 v[50:53], v254
	ds_read_b128 v[54:57], v254 offset:4096
	ds_read_b128 v[58:61], v255
	ds_read_b128 v[62:65], v255 offset:4096
	ds_read_b128 v[106:109], v190 offset:8192
	ds_read_b128 v[110:113], v190 offset:8704
	ds_read_b128 v[114:117], v190 offset:10240
	ds_read_b128 v[118:121], v190 offset:10752
	s_waitcnt lgkmcnt(11)
	v_mfma_f32_32x32x16_bf16 v[18:33], v[2:5], v[82:85], v[66:81]
	s_waitcnt lgkmcnt(10)
	v_mfma_f32_32x32x16_bf16 v[34:49], v[6:9], v[82:85], v[66:81]
	s_waitcnt lgkmcnt(9)
	v_mfma_f32_32x32x16_bf16 v[18:33], v[10:13], v[86:89], v[18:33]
	s_waitcnt lgkmcnt(8)
	v_mfma_f32_32x32x16_bf16 v[34:49], v[14:17], v[86:89], v[34:49]
	s_waitcnt lgkmcnt(7)
	v_mfma_f32_32x32x16_bf16 v[18:33], v[50:53], v[90:93], v[18:33]
	s_waitcnt lgkmcnt(6)
	v_mfma_f32_32x32x16_bf16 v[34:49], v[54:57], v[90:93], v[34:49]
	s_waitcnt lgkmcnt(5)
	v_mfma_f32_32x32x16_bf16 v[18:33], v[58:61], v[94:97], v[18:33]
	s_waitcnt lgkmcnt(4)
	v_mfma_f32_32x32x16_bf16 v[34:49], v[62:65], v[94:97], v[34:49]
	s_waitcnt lgkmcnt(3)
	v_mfma_f32_32x32x16_bf16 v[18:33], v[106:109], v[98:101], v[18:33]
	s_waitcnt lgkmcnt(2)
	v_mfma_f32_32x32x16_bf16 v[34:49], v[110:113], v[98:101], v[34:49]
	s_waitcnt lgkmcnt(1)
	v_mfma_f32_32x32x16_bf16 v[18:33], v[114:117], v[102:105], v[18:33]
	s_waitcnt lgkmcnt(0)
	v_mfma_f32_32x32x16_bf16 v[34:49], v[118:121], v[102:105], v[34:49]
	s_nop 15
	s_nop 7
	s_branch .LBB13_751

; #define AT_WAIT_BAR(N) asm volatile("s_waitcnt vmcnt(" #N ") lgkmcnt(0)\n\ts_barrier" ::: "memory")
; template <int THRL>
; __device__ __forceinline__ void attn_item(int b, int h, int s, const bf16_t* Q, const bf16_t* KN, const bf16_t* KR, const bf16_t* V, const float* goa  , bf16_t* Y, float* ssqy, AT_LAS char* shm, int wid0) {
;     ...
;         const int qb = (ui == 0) ? s : (ui == 1) ? 7 - s : (ui == 2) ? 2 + s : 5 - s; const int q0 = qb * 256;
;         const int NT = (q0 + 256) / KVBLK;
;         float mhat = 0.f, l_reg = 0.f; f32x16 o[2]; o[0] = f32x16{}; o[1] = f32x16{};
;         f32x16 negm = f32x16{}; asm volatile("" : "+v"(negm));
;         u32x4 pw0 = u32x4{}, pw1 = u32x4{}, pw2 = u32x4{}, pw3 = u32x4{}; bool have = false;
;         f32x16 p0 = f32x16{}, p1 = f32x16{};
;         AT_WAIT_BAR(6);
;         if (!late) qkt(p0, p1, kp0, qr, negm);
;         for (int t = 0; t < NT; ++t) {
;             AT_WAIT_BAR(3);
;             AT_DMA(t + 3, t + 2, NT);
;             const int jb = t - (NT - 4);
;             const bool need = jb <= wq;
;             if (late) { if (have) pv(o, vp0 + ((t - 1) & 3) * VSLOTB, pw0, pw1, pw2, pw3);
;                         have = false; if (need) qkt(p0, p1, kp0 + (t & 3) * KSLOTB, qr, negm); }
.LBB13_751:
	s_cmp_eq_u32 s8, 2
	v_readlane_b32 s3, v238, 57
	s_cselect_b32 s3, s3, s86
	s_cmp_eq_u32 s8, 1
	s_cselect_b64 s[82:83], -1, 0
	s_and_b64 s[4:5], s[82:83], exec
	v_readlane_b32 s4, v238, 59
	s_cselect_b32 s3, s4, s3
	s_cmp_eq_u32 s8, 0
	s_cselect_b64 s[94:95], -1, 0
	s_and_b64 s[4:5], s[94:95], exec
	v_readlane_b32 s4, v238, 58
	s_cselect_b32 s3, s4, s3
	s_lshl_b32 s4, s3, 8
	s_add_i32 s5, s4, 0x100
	s_lshr_b32 s79, s5, 6
	v_readlane_b32 s80, v238, 16
	v_readlane_b32 s5, v238, 52
	s_waitcnt vmcnt(3) lgkmcnt(0)
	s_barrier
	s_add_i32 s5, s5, s80
	s_mov_b32 s9, m0
	s_mov_b32 m0, s5
	s_nop 0
	global_load_lds_dwordx4 v[144:145], off
	s_mov_b32 m0, s9
	v_readlane_b32 s5, v238, 54
	s_add_i32 s5, s5, s80
	s_mov_b32 s9, m0
	s_mov_b32 m0, s5
	s_nop 0
	global_load_lds_dwordx4 v[146:147], off
	s_mov_b32 m0, s9
	s_add_i32 s9, s33, 0x10000
	s_sub_i32 s5, 4, s79
	s_cmp_le_i32 s5, s2
	s_cselect_b64 s[92:93], -1, 0
	s_and_b64 s[80:81], s[0:1], s[92:93]
	s_andn2_b64 vcc, exec, s[80:81]
	s_mov_b32 s80, m0
	s_mov_b32 m0, s9
	s_nop 0
	global_load_lds_dwordx4 v[148:149], off
	s_mov_b32 m0, s80
	s_cbranch_vccnz .LBB13_753
	ds_read_b128 v[2:5], v252
	ds_read_b128 v[6:9], v252 offset:4096
	ds_read_b128 v[10:13], v253
	ds_read_b128 v[14:17], v253 offset:4096
	ds_read_b128 v[50:53], v254
	ds_read_b128 v[54:57], v254 offset:4096
	ds_read_b128 v[58:61], v255
	ds_read_b128 v[62:65], v255 offset:4096
	ds_read_b128 v[106:109], v190 offset:8192
	ds_read_b128 v[110:113], v190 offset:8704
	ds_read_b128 v[114:117], v190 offset:10240
	ds_read_b128 v[118:121], v190 offset:10752
	s_waitcnt lgkmcnt(11)
	v_mfma_f32_32x32x16_bf16 v[18:33], v[2:5], v[82:85], v[66:81]
	s_waitcnt lgkmcnt(10)
	v_mfma_f32_32x32x16_bf16 v[34:49], v[6:9], v[82:85], v[66:81]
	s_waitcnt lgkmcnt(9)
	v_mfma_f32_32x32x16_bf16 v[18:33], v[10:13], v[86:89], v[18:33]
	s_waitcnt lgkmcnt(8)
	v_mfma_f32_32x32x16_bf16 v[34:49], v[14:17], v[86:89], v[34:49]
	s_waitcnt lgkmcnt(7)
	v_mfma_f32_32x32x16_bf16 v[18:33], v[50:53], v[90:93], v[18:33]
	s_waitcnt lgkmcnt(6)
	v_mfma_f32_32x32x16_bf16 v[34:49], v[54:57], v[90:93], v[34:49]
	s_waitcnt lgkmcnt(5)
	v_mfma_f32_32x32x16_bf16 v[18:33], v[58:61], v[94:97], v[18:33]
	s_waitcnt lgkmcnt(4)
	v_mfma_f32_32x32x16_bf16 v[34:49], v[62:65], v[94:97], v[34:49]
	s_waitcnt lgkmcnt(3)
	v_mfma_f32_32x32x16_bf16 v[18:33], v[106:109], v[98:101], v[18:33]
	s_waitcnt lgkmcnt(2)
	v_mfma_f32_32x32x16_bf16 v[34:49], v[110:113], v[98:101], v[34:49]
	s_waitcnt lgkmcnt(1)
	v_mfma_f32_32x32x16_bf16 v[18:33], v[114:117], v[102:105], v[18:33]
	s_waitcnt lgkmcnt(0)
	v_mfma_f32_32x32x16_bf16 v[34:49], v[118:121], v[102:105], v[34:49]
	s_nop 15
	s_nop 7

; #define AT_LAS __attribute__((address_space(3)))
; __device__ __forceinline__ void qkt(f32x16& p0, f32x16& p1, AT_LAS const char* kb, const bf16x8 (&qr)[6], const f32x16& negm) {
;     bf16x8 kf[12];
; #pragma unroll
;     for (int d0 = 0; d0 < 6; ++d0) { kf[2 * d0] = *(AT_LAS const bf16x8*)(kb + d0 * 2048); kf[2 * d0 + 1] = *(AT_LAS const bf16x8*)(kb + d0 * 2048 + 512); }
;     __builtin_amdgcn_sched_barrier(0);
;     p0 = __builtin_amdgcn_mfma_f32_32x32x16_bf16(kf[0], qr[0], negm, 0, 0, 0); p1 = __builtin_amdgcn_mfma_f32_32x32x16_bf16(kf[1], qr[0], negm, 0, 0, 0);
; #pragma unroll
;     for (int d0 = 1; d0 < 6; ++d0) { p0 = __builtin_amdgcn_mfma_f32_32x32x16_bf16(kf[2 * d0], qr[d0], p0, 0, 0, 0); p1 = __builtin_amdgcn_mfma_f32_32x32x16_bf16(kf[2 * d0 + 1], qr[d0], p1, 0, 0, 0); }
;     asm volatile("s_nop 15\n\ts_nop 7" : "+v"(p0), "+v"(p1));
; }
; template <int THRL>
; __device__ __forceinline__ void attn_item(int b, int h, int s, const bf16_t* Q, const bf16_t* KN, const bf16_t* KR, const bf16_t* V, const float* goa  , bf16_t* Y, float* ssqy, AT_LAS char* shm, int wid0) {
;     ...
;             if (!late) { if (t + 1 < NT && (jb + 1) <= wq) qkt(p0, p1, kp0 + ((t + 1) & 3) * KSLOTB, qr, negm); }
.LBB13_761:
	s_cmp_ge_i32 s5, s2
	s_cselect_b64 s[80:81], -1, 0
	s_or_b64 s[80:81], s[0:1], s[80:81]
	s_andn2_b64 vcc, exec, s[80:81]
	s_cbranch_vccz .LBB13_763
	ds_read_b128 v[34:37], v252 offset:12288
	ds_read_b128 v[154:157], v252 offset:16384
	ds_read_b128 v[158:161], v253 offset:12288
	ds_read_b128 v[162:165], v253 offset:16384
	ds_read_b128 v[166:169], v254 offset:12288
	ds_read_b128 v[170:173], v254 offset:16384
	ds_read_b128 v[174:177], v255 offset:12288
	ds_read_b128 v[178:181], v255 offset:16384
	ds_read_b128 v[198:201], v190 offset:20480
	ds_read_b128 v[202:205], v190 offset:20992
	ds_read_b128 v[206:209], v190 offset:22528
	ds_read_b128 v[210:213], v190 offset:23040
	s_waitcnt lgkmcnt(11)
	v_mfma_f32_32x32x16_bf16 v[18:33], v[34:37], v[82:85], v[66:81]
	s_waitcnt lgkmcnt(10)
	v_mfma_f32_32x32x16_bf16 v[34:49], v[154:157], v[82:85], v[66:81]
	s_waitcnt lgkmcnt(9)
	v_mfma_f32_32x32x16_bf16 v[18:33], v[158:161], v[86:89], v[18:33]
	s_waitcnt lgkmcnt(8)
	v_mfma_f32_32x32x16_bf16 v[34:49], v[162:165], v[86:89], v[34:49]
	s_waitcnt lgkmcnt(7)
	v_mfma_f32_32x32x16_bf16 v[18:33], v[166:169], v[90:93], v[18:33]
	s_waitcnt lgkmcnt(6)
	v_mfma_f32_32x32x16_bf16 v[34:49], v[170:173], v[90:93], v[34:49]
	s_waitcnt lgkmcnt(5)
	v_mfma_f32_32x32x16_bf16 v[18:33], v[174:177], v[94:97], v[18:33]
	s_waitcnt lgkmcnt(4)
	v_mfma_f32_32x32x16_bf16 v[34:49], v[178:181], v[94:97], v[34:49]
	s_waitcnt lgkmcnt(3)
	v_mfma_f32_32x32x16_bf16 v[18:33], v[198:201], v[98:101], v[18:33]
	s_waitcnt lgkmcnt(2)
	v_mfma_f32_32x32x16_bf16 v[34:49], v[202:205], v[98:101], v[34:49]
	s_waitcnt lgkmcnt(1)
	v_mfma_f32_32x32x16_bf16 v[18:33], v[206:209], v[102:105], v[18:33]
	s_waitcnt lgkmcnt(0)
	v_mfma_f32_32x32x16_bf16 v[34:49], v[210:213], v[102:105], v[34:49]
	s_nop 15
	s_nop 7

; #define AT_LAS __attribute__((address_space(3)))
; __device__ __forceinline__ s16x4 vtr(AT_LAS const char* p) { return __builtin_bit_cast(s16x4, __builtin_amdgcn_ds_read_tr16_b64_v4i16((AT_LAS v4i16_t*)p)); }
; __device__ __forceinline__ void pv(f32x16 (&o)[2], AT_LAS const char* vp, const u32x4& pw0, const u32x4& pw1, const u32x4& pw2, const u32x4& pw3) {
; #pragma unroll
;     for (int d0 = 0; d0 < 2; ++d0) { s16x4 lo[4], hh[4];
; #pragma unroll
;         for (int ks = 0; ks < 4; ++ks) { lo[ks] = vtr(vp + d0 * 4096 + ks * 1024); hh[ks] = vtr(vp + d0 * 4096 + ks * 1024 + 512); }
;     ...
;         o[d0] = __builtin_amdgcn_mfma_f32_32x32x16_bf16(__builtin_bit_cast(bf16x8, pw0), AT_VF(0), o[d0], 0, 0, 0);
;         o[d0] = __builtin_amdgcn_mfma_f32_32x32x16_bf16(__builtin_bit_cast(bf16x8, pw1), AT_VF(1), o[d0], 0, 0, 0);
;         o[d0] = __builtin_amdgcn_mfma_f32_32x32x16_bf16(__builtin_bit_cast(bf16x8, pw2), AT_VF(2), o[d0], 0, 0, 0);
;         o[d0] = __builtin_amdgcn_mfma_f32_32x32x16_bf16(__builtin_bit_cast(bf16x8, pw3), AT_VF(3), o[d0], 0, 0, 0);
;     ...
;     }
; }
; __device__ __forceinline__ void qkt(f32x16& p0, f32x16& p1, AT_LAS const char* kb, const bf16x8 (&qr)[6], const f32x16& negm) {
;     bf16x8 kf[12];
; #pragma unroll
;     for (int d0 = 0; d0 < 6; ++d0) { kf[2 * d0] = *(AT_LAS const bf16x8*)(kb + d0 * 2048); kf[2 * d0 + 1] = *(AT_LAS const bf16x8*)(kb + d0 * 2048 + 512); }
;     __builtin_amdgcn_sched_barrier(0);
;     p0 = __builtin_amdgcn_mfma_f32_32x32x16_bf16(kf[0], qr[0], negm, 0, 0, 0); p1 = __builtin_amdgcn_mfma_f32_32x32x16_bf16(kf[1], qr[0], negm, 0, 0, 0);
; #pragma unroll
;     for (int d0 = 1; d0 < 6; ++d0) { p0 = __builtin_amdgcn_mfma_f32_32x32x16_bf16(kf[2 * d0], qr[d0], p0, 0, 0, 0); p1 = __builtin_amdgcn_mfma_f32_32x32x16_bf16(kf[2 * d0 + 1], qr[d0], p1, 0, 0, 0); }
;     asm volatile("s_nop 15\n\ts_nop 7" : "+v"(p0), "+v"(p1));
; }
; template <int THRL>
; __device__ __forceinline__ void attn_item(int b, int h, int s, const bf16_t* Q, const bf16_t* KN, const bf16_t* KR, const bf16_t* V, const float* goa  , bf16_t* Y, float* ssqy, AT_LAS char* shm, int wid0) {
;     ...
;             if (late) { if (have) pv(o, vp0 + ((t - 1) & 3) * VSLOTB, pw0, pw1, pw2, pw3);
;                         have = false; if (need) qkt(p0, p1, kp0 + (t & 3) * KSLOTB, qr, negm); }
.LBB13_768:
	s_and_b64 vcc, s[96:97], s[92:93]
	s_cbranch_vccz .Lat0_l_slow
	s_and_b32 s88, s80, 0x6000
	v_add_u32_e32 v214, s88, v191
	s_add_i32 s88, s9, -3
	s_and_b32 s88, s88, 3
	s_mulk_i32 s88, 0x3000
	v_add_u32_e32 v215, s88, v190
	ds_read_b64_tr_b16 v[216:217], v214 offset:49152
	ds_read_b64_tr_b16 v[218:219], v214 offset:49664
	ds_read_b64_tr_b16 v[220:221], v214 offset:50176
	ds_read_b64_tr_b16 v[222:223], v214 offset:50688
	ds_read_b64_tr_b16 v[224:225], v214 offset:51200
	ds_read_b64_tr_b16 v[226:227], v214 offset:51712
	ds_read_b64_tr_b16 v[228:229], v214 offset:52224
	ds_read_b64_tr_b16 v[230:231], v214 offset:52736
	ds_read_b64_tr_b16 v[232:233], v214 offset:53248
	ds_read_b64_tr_b16 v[234:235], v214 offset:53760
	ds_read_b64_tr_b16 v[240:241], v214 offset:54272
	ds_read_b64_tr_b16 v[242:243], v214 offset:54784
	ds_read_b64_tr_b16 v[244:245], v214 offset:55296
	ds_read_b64_tr_b16 v[246:247], v214 offset:55808
	ds_read_b64_tr_b16 v[248:249], v214 offset:56320
	s_waitcnt lgkmcnt(13)
	v_mfma_f32_32x32x16_bf16 v[50:65], v[110:113], v[216:219], v[50:65]
	ds_read_b64_tr_b16 v[250:251], v214 offset:56832
	v_add_u32_e32 v236, s88, v252
	ds_read_b128 v[34:37], v236
	s_waitcnt lgkmcnt(13)
	v_mfma_f32_32x32x16_bf16 v[50:65], v[106:109], v[220:223], v[50:65]
	ds_read_b128 v[154:157], v236 offset:4096
	v_add_u32_e32 v239, s88, v253
	ds_read_b128 v[158:161], v239
	s_waitcnt lgkmcnt(13)
	v_mfma_f32_32x32x16_bf16 v[50:65], v[118:121], v[224:227], v[50:65]
	ds_read_b128 v[162:165], v239 offset:4096
	v_add_u32_e32 v236, s88, v254
	ds_read_b128 v[166:169], v236
	s_waitcnt lgkmcnt(13)
	v_mfma_f32_32x32x16_bf16 v[50:65], v[114:117], v[228:231], v[50:65]
	ds_read_b128 v[170:173], v236 offset:4096
	v_add_u32_e32 v239, s88, v255
	ds_read_b128 v[174:177], v239
	s_waitcnt lgkmcnt(13)
	v_mfma_f32_32x32x16_bf16 v[2:17], v[110:113], v[232:235], v[2:17]
	ds_read_b128 v[178:181], v239 offset:4096
	ds_read_b128 v[198:201], v215 offset:8192
	s_waitcnt lgkmcnt(13)
	v_mfma_f32_32x32x16_bf16 v[2:17], v[106:109], v[240:243], v[2:17]
	ds_read_b128 v[202:205], v215 offset:8704
	ds_read_b128 v[206:209], v215 offset:10240
	s_waitcnt lgkmcnt(13)
	v_mfma_f32_32x32x16_bf16 v[2:17], v[118:121], v[244:247], v[2:17]
	ds_read_b128 v[210:213], v215 offset:10752
	s_waitcnt lgkmcnt(12)
	v_mfma_f32_32x32x16_bf16 v[2:17], v[114:117], v[248:251], v[2:17]
	s_waitcnt lgkmcnt(11)
	v_mfma_f32_32x32x16_bf16 v[18:33], v[34:37], v[82:85], v[66:81]
	s_waitcnt lgkmcnt(10)
	v_mfma_f32_32x32x16_bf16 v[34:49], v[154:157], v[82:85], v[66:81]
	s_waitcnt lgkmcnt(9)
	v_mfma_f32_32x32x16_bf16 v[18:33], v[158:161], v[86:89], v[18:33]
	s_waitcnt lgkmcnt(8)
	v_mfma_f32_32x32x16_bf16 v[34:49], v[162:165], v[86:89], v[34:49]
	s_waitcnt lgkmcnt(7)
	v_mfma_f32_32x32x16_bf16 v[18:33], v[166:169], v[90:93], v[18:33]
	s_waitcnt lgkmcnt(6)
	v_mfma_f32_32x32x16_bf16 v[34:49], v[170:173], v[90:93], v[34:49]
	s_waitcnt lgkmcnt(5)
	v_mfma_f32_32x32x16_bf16 v[18:33], v[174:177], v[94:97], v[18:33]
	s_waitcnt lgkmcnt(4)
	v_mfma_f32_32x32x16_bf16 v[34:49], v[178:181], v[94:97], v[34:49]
	s_waitcnt lgkmcnt(3)
	v_mfma_f32_32x32x16_bf16 v[18:33], v[198:201], v[98:101], v[18:33]
	s_waitcnt lgkmcnt(2)
	v_mfma_f32_32x32x16_bf16 v[34:49], v[202:205], v[98:101], v[34:49]
	s_waitcnt lgkmcnt(1)
	v_mfma_f32_32x32x16_bf16 v[18:33], v[206:209], v[102:105], v[18:33]
	s_waitcnt lgkmcnt(0)
	v_mfma_f32_32x32x16_bf16 v[34:49], v[210:213], v[102:105], v[34:49]
	s_mov_b64 s[96:97], 0
	s_nop 7
	s_nop 3
	s_branch .LBB13_773

; #define AT_LAS __attribute__((address_space(3)))
; __device__ __forceinline__ void qkt(f32x16& p0, f32x16& p1, AT_LAS const char* kb, const bf16x8 (&qr)[6], const f32x16& negm) {
;     bf16x8 kf[12];
; #pragma unroll
;     for (int d0 = 0; d0 < 6; ++d0) { kf[2 * d0] = *(AT_LAS const bf16x8*)(kb + d0 * 2048); kf[2 * d0 + 1] = *(AT_LAS const bf16x8*)(kb + d0 * 2048 + 512); }
;     __builtin_amdgcn_sched_barrier(0);
;     p0 = __builtin_amdgcn_mfma_f32_32x32x16_bf16(kf[0], qr[0], negm, 0, 0, 0); p1 = __builtin_amdgcn_mfma_f32_32x32x16_bf16(kf[1], qr[0], negm, 0, 0, 0);
; #pragma unroll
;     for (int d0 = 1; d0 < 6; ++d0) { p0 = __builtin_amdgcn_mfma_f32_32x32x16_bf16(kf[2 * d0], qr[d0], p0, 0, 0, 0); p1 = __builtin_amdgcn_mfma_f32_32x32x16_bf16(kf[2 * d0 + 1], qr[d0], p1, 0, 0, 0); }
;     asm volatile("s_nop 15\n\ts_nop 7" : "+v"(p0), "+v"(p1));
; }
; template <int THRL>
; __device__ __forceinline__ void attn_item(int b, int h, int s, const bf16_t* Q, const bf16_t* KN, const bf16_t* KR, const bf16_t* V, const float* goa  , bf16_t* Y, float* ssqy, AT_LAS char* shm, int wid0) {
;     ...
;             if (late) { if (have) pv(o, vp0 + ((t - 1) & 3) * VSLOTB, pw0, pw1, pw2, pw3);
;                         have = false; if (need) qkt(p0, p1, kp0 + (t & 3) * KSLOTB, qr, negm); }
.LBB13_770:
	s_andn2_b64 vcc, exec, s[92:93]
	s_cbranch_vccnz .LBB13_772
	s_add_i32 s88, s9, -3
	s_and_b32 s88, s88, 3
	s_mulk_i32 s88, 0x3000
	v_add_u32_e32 v0, s88, v190
	v_add_u32_e32 v236, s88, v252
	ds_read_b128 v[34:37], v236
	ds_read_b128 v[154:157], v236 offset:4096
	v_add_u32_e32 v239, s88, v253
	ds_read_b128 v[158:161], v239
	ds_read_b128 v[162:165], v239 offset:4096
	v_add_u32_e32 v236, s88, v254
	ds_read_b128 v[166:169], v236
	ds_read_b128 v[170:173], v236 offset:4096
	v_add_u32_e32 v239, s88, v255
	ds_read_b128 v[174:177], v239
	ds_read_b128 v[178:181], v239 offset:4096
	ds_read_b128 v[198:201], v0 offset:8192
	ds_read_b128 v[202:205], v0 offset:8704
	ds_read_b128 v[206:209], v0 offset:10240
	ds_read_b128 v[210:213], v0 offset:10752
	s_waitcnt lgkmcnt(11)
	v_mfma_f32_32x32x16_bf16 v[18:33], v[34:37], v[82:85], v[66:81]
	s_waitcnt lgkmcnt(10)
	v_mfma_f32_32x32x16_bf16 v[34:49], v[154:157], v[82:85], v[66:81]
	s_waitcnt lgkmcnt(9)
	v_mfma_f32_32x32x16_bf16 v[18:33], v[158:161], v[86:89], v[18:33]
	s_waitcnt lgkmcnt(8)
	v_mfma_f32_32x32x16_bf16 v[34:49], v[162:165], v[86:89], v[34:49]
	s_waitcnt lgkmcnt(7)
	v_mfma_f32_32x32x16_bf16 v[18:33], v[166:169], v[90:93], v[18:33]
	s_waitcnt lgkmcnt(6)
	v_mfma_f32_32x32x16_bf16 v[34:49], v[170:173], v[90:93], v[34:49]
	s_waitcnt lgkmcnt(5)
	v_mfma_f32_32x32x16_bf16 v[18:33], v[174:177], v[94:97], v[18:33]
	s_waitcnt lgkmcnt(4)
	v_mfma_f32_32x32x16_bf16 v[34:49], v[178:181], v[94:97], v[34:49]
	s_waitcnt lgkmcnt(3)
	v_mfma_f32_32x32x16_bf16 v[18:33], v[198:201], v[98:101], v[18:33]
	s_waitcnt lgkmcnt(2)
	v_mfma_f32_32x32x16_bf16 v[34:49], v[202:205], v[98:101], v[34:49]
	s_waitcnt lgkmcnt(1)
	v_mfma_f32_32x32x16_bf16 v[18:33], v[206:209], v[102:105], v[18:33]
	s_waitcnt lgkmcnt(0)
	v_mfma_f32_32x32x16_bf16 v[34:49], v[210:213], v[102:105], v[34:49]
	s_nop 15
	s_nop 7

; template <int THRL>
; __device__ __forceinline__ void attn_item(int b, int h, int s, const bf16_t* Q, const bf16_t* KN, const bf16_t* KR, const bf16_t* V, const float* goa  , bf16_t* Y, float* ssqy, AT_LAS char* shm, int wid0) {
;     ...
;                 float sacc = 0.f;
; #pragma unroll
;                 for (int r = 0; r < 16; ++r) { p0[r] = __builtin_amdgcn_exp2f(p0[r]); p1[r] = __builtin_amdgcn_exp2f(p1[r]); sacc += p0[r] + p1[r]; }
;                 l_reg += sacc;
;     ...
;             if (!late) { if (t + 1 < NT && (jb + 1) <= wq) qkt(p0, p1, kp0 + ((t + 1) & 3) * KSLOTB, qr, negm); }
.LBB13_782:
	v_add_f32_e32 v18, v18, v34
	v_add_f32_e32 v0, v0, v154
	v_add_f32_e32 v20, v20, v36
	v_add_f32_e32 v168, v168, v156
	v_add_f32_e32 v22, v22, v38
	v_add_f32_e32 v170, v170, v158
	v_add_f32_e32 v24, v24, v40
	v_add_f32_e32 v172, v172, v160
	v_add_f32_e32 v26, v26, v42
	v_add_f32_e32 v174, v174, v162
	v_add_f32_e32 v28, v28, v44
	v_add_f32_e32 v176, v176, v164
	v_add_f32_e32 v30, v30, v46
	v_add_f32_e32 v178, v178, v166
	v_add_f32_e32 v32, v32, v48
	v_add_f32_e32 v33, v33, v49
	v_add_f32_e32 v18, v18, v0
	v_add_f32_e32 v20, v20, v168
	v_add_f32_e32 v22, v22, v170
	v_add_f32_e32 v24, v24, v172
	v_add_f32_e32 v26, v26, v174
	v_add_f32_e32 v28, v28, v176
	v_add_f32_e32 v30, v30, v178
	v_add_f32_e32 v32, v32, v33
	v_add_f32_e32 v18, v18, v20
	v_add_f32_e32 v22, v22, v24
	v_add_f32_e32 v26, v26, v28
	v_add_f32_e32 v30, v30, v32
	v_add_f32_e32 v18, v18, v22
	v_add_f32_e32 v26, v26, v30
	v_add_f32_e32 v0, v18, v26
	v_add_f32_e32 v153, v153, v0
	s_and_b64 vcc, exec, s[76:77]
	s_cbranch_vccnz .LBB13_764
.LBB13_783:
	s_add_i32 s92, s9, -2
	s_cmp_lt_u32 s92, s79
	s_cselect_b64 vcc, -1, 0
	s_cmp_lt_i32 s84, s2
	s_cselect_b64 s[88:89], -1, 0
	s_and_b64 s[88:89], vcc, s[88:89]
	s_andn2_b64 vcc, exec, s[88:89]
	s_cbranch_vccnz .LBB13_764
	s_and_b32 s84, s92, 3
	s_mulk_i32 s84, 0x3000
	v_add_u32_e32 v0, s84, v190
	v_add_u32_e32 v236, s84, v252
	ds_read_b128 v[34:37], v236
	ds_read_b128 v[154:157], v236 offset:4096
	v_add_u32_e32 v239, s84, v253
	ds_read_b128 v[158:161], v239
	ds_read_b128 v[162:165], v239 offset:4096
	v_add_u32_e32 v236, s84, v254
	ds_read_b128 v[166:169], v236
	ds_read_b128 v[170:173], v236 offset:4096
	v_add_u32_e32 v239, s84, v255
	ds_read_b128 v[174:177], v239
	ds_read_b128 v[178:181], v239 offset:4096
	ds_read_b128 v[198:201], v0 offset:8192
	ds_read_b128 v[202:205], v0 offset:8704
	ds_read_b128 v[206:209], v0 offset:10240
	ds_read_b128 v[210:213], v0 offset:10752
	s_waitcnt lgkmcnt(11)
	v_mfma_f32_32x32x16_bf16 v[18:33], v[34:37], v[82:85], v[66:81]
	s_waitcnt lgkmcnt(10)
	v_mfma_f32_32x32x16_bf16 v[34:49], v[154:157], v[82:85], v[66:81]
	s_waitcnt lgkmcnt(9)
	v_mfma_f32_32x32x16_bf16 v[18:33], v[158:161], v[86:89], v[18:33]
	s_waitcnt lgkmcnt(8)
	v_mfma_f32_32x32x16_bf16 v[34:49], v[162:165], v[86:89], v[34:49]
	s_waitcnt lgkmcnt(7)
	v_mfma_f32_32x32x16_bf16 v[18:33], v[166:169], v[90:93], v[18:33]
	s_waitcnt lgkmcnt(6)
	v_mfma_f32_32x32x16_bf16 v[34:49], v[170:173], v[90:93], v[34:49]
	s_waitcnt lgkmcnt(5)
	v_mfma_f32_32x32x16_bf16 v[18:33], v[174:177], v[94:97], v[18:33]
	s_waitcnt lgkmcnt(4)
	v_mfma_f32_32x32x16_bf16 v[34:49], v[178:181], v[94:97], v[34:49]
	s_waitcnt lgkmcnt(3)
	v_mfma_f32_32x32x16_bf16 v[18:33], v[198:201], v[98:101], v[18:33]
	s_waitcnt lgkmcnt(2)
	v_mfma_f32_32x32x16_bf16 v[34:49], v[202:205], v[98:101], v[34:49]
	s_waitcnt lgkmcnt(1)
	v_mfma_f32_32x32x16_bf16 v[18:33], v[206:209], v[102:105], v[18:33]
	s_waitcnt lgkmcnt(0)
	v_mfma_f32_32x32x16_bf16 v[34:49], v[210:213], v[102:105], v[34:49]
	s_branch .LBB13_764

; __device__ __forceinline__ u32x4 pack8(const f32x4& a, const f32x4& b) { u32x4 w; w.x = cvt_pk_bf16(a[0], a[1]); w.y = cvt_pk_bf16(a[2], a[3]); w.z = cvt_pk_bf16(b[0], b[1]); w.w = cvt_pk_bf16(b[2], b[3]); return w; }
; __device__ __forceinline__ float hsq4(const f32x4& a) { return (a[0] * a[0] + a[1] * a[1]) + (a[2] * a[2] + a[3] * a[3]); }
; #define AT_LAS __attribute__((address_space(3)))
; #define AT_QLOAD(dst, qb_) do { const bf16_t* Qw_ = Q + (rowbase + (qb_) * 256 + wid * 32) * 768 + h * 96; \
;         _Pragma("unroll") for (int d0 = 0; d0 < 6; ++d0) dst[d0] = *(const bf16x8*)(Qw_ + (size_t)r32 * 768 + d0 * 16 + hi * 8); } while (0)
; template <int THRL>
; __device__ __forceinline__ void attn_item(int b, int h, int s, const bf16_t* Q, const bf16_t* KN, const bf16_t* KR, const bf16_t* V, const float* goa  , bf16_t* Y, float* ssqy, AT_LAS char* shm, int wid0) {
;     ...
;         asm volatile("s_waitcnt vmcnt(0) lgkmcnt(0)\n\ts_barrier" ::: "memory");
;         if (ui < 3) {
;             const int qbn = (ui == 0) ? 7 - s : (ui == 1) ? 2 + s : 5 - s; const int NTn = 4 * qbn + 4;
;             AT_QLOAD(qr, qbn); AT_DMA(0, 0, NTn); AT_DMA(1, 1, NTn); AT_DMA(2, 1, NTn); }
;     ...
;             const float* gp = goa + h * 64 + d0 * 32 + half * 16; bf16_t* yp = Y + grow * YLD + 512 + h * 64 + d0 * 32 + half * 16;
; #pragma unroll
;             for (int i = 0; i < 2; ++i) { const f32x4 a = *(AT_LAS const f32x4*)(stg + row * OROW + half * 64 + i * 32), c = *(AT_LAS const f32x4*)(stg + row * OROW + half * 64 + i * 32 + 16);
;                 ss += pg8::hsq4(a) + pg8::hsq4(c);
;                 *(u32x4*)(yp + i * 8) = pg8::pack8(a * *(const f32x4*)(gp + i * 8), c * *(const f32x4*)(gp + i * 8 + 4)); }
.LBB13_787:
	s_waitcnt vmcnt(0) lgkmcnt(0)
	s_barrier
	global_load_dwordx4 v[216:219], v[142:143], off offset:16
	global_load_dwordx4 v[220:223], v[142:143], off
	global_load_dwordx4 v[224:227], v[142:143], off offset:48
	global_load_dwordx4 v[228:231], v[142:143], off offset:32
	global_load_dwordx4 v[232:235], v[142:143], off offset:144
	global_load_dwordx4 v[240:243], v[142:143], off offset:128
	global_load_dwordx4 v[244:247], v[142:143], off offset:176
	global_load_dwordx4 v[248:251], v[142:143], off offset:160
	s_cmp_eq_u32 s8, 3
	s_cbranch_scc1 .Lat0_lastu
	s_and_b64 s[76:77], s[82:83], exec
	v_readlane_b32 s3, v238, 57
	s_cselect_b32 s3, s3, s86
	s_and_b64 s[76:77], s[94:95], exec
	v_readlane_b32 s5, v238, 59
	s_cselect_b32 s3, s5, s3
	s_lshl_b32 s3, s3, 8
	v_readlane_b32 s5, v238, 60
	s_add_u32 s3, s5, s3
	v_readlane_b32 s5, v238, 61
	s_addc_u32 s5, s5, 0
	s_mulk_i32 s5, 0x600
	v_mad_u64_u32 v[18:19], s[76:77], s3, v189, v[138:139]
	v_add_u32_e32 v19, s5, v19
	global_load_dwordx4 v[82:85], v[18:19], off
	global_load_dwordx4 v[86:89], v[18:19], off offset:32
	global_load_dwordx4 v[90:93], v[18:19], off offset:64
	global_load_dwordx4 v[94:97], v[18:19], off offset:96
	global_load_dwordx4 v[98:101], v[18:19], off offset:128
	global_load_dwordx4 v[102:105], v[18:19], off offset:160
	s_mov_b32 s3, m0
	s_mov_b32 m0, s33
	s_nop 0
	global_load_lds_dwordx4 v[122:123], off
	s_mov_b32 m0, s3
	v_readlane_b32 s5, v238, 50
	s_mov_b32 s3, m0
	s_mov_b32 m0, s78
	s_nop 0
	global_load_lds_dwordx4 v[124:125], off
	s_mov_b32 m0, s3
	v_readlane_b32 s9, v238, 53
	s_mov_b32 s3, m0
	s_mov_b32 m0, s87
	s_nop 0
	global_load_lds_dwordx4 v[126:127], off
	s_mov_b32 m0, s3
	s_nop 0
	s_mov_b32 s3, m0
	s_mov_b32 m0, s5
	s_nop 0
	global_load_lds_dwordx4 v[128:129], off
	s_mov_b32 m0, s3
	v_readlane_b32 s5, v238, 51
	s_mov_b32 s3, m0
	s_mov_b32 m0, s5
	s_nop 0
	global_load_lds_dwordx4 v[130:131], off
	s_mov_b32 m0, s3
	v_readlane_b32 s5, v238, 56
	s_mov_b32 s3, m0
	s_mov_b32 m0, s5
	s_nop 0
	global_load_lds_dwordx4 v[132:133], off
	s_mov_b32 m0, s3
	s_nop 0
	s_mov_b32 s3, m0
	s_mov_b32 m0, s9
	s_nop 0
	global_load_lds_dwordx4 v[134:135], off
	s_mov_b32 m0, s3
	v_readlane_b32 s9, v238, 55
	s_mov_b32 s3, m0
	s_mov_b32 m0, s9
	s_nop 0
	global_load_lds_dwordx4 v[136:137], off
	s_mov_b32 m0, s3
	s_nop 0
	s_mov_b32 s3, m0
	s_mov_b32 m0, s5
	s_nop 0
	global_load_lds_dwordx4 v[132:133], off
	s_mov_b32 m0, s3

; __device__ __forceinline__ float swz_xor1(float v) { return __int_as_float(__builtin_amdgcn_ds_swizzle(__float_as_int(v), 0x041F)); }
; __device__ __forceinline__ u32x4 pack8(const f32x4& a, const f32x4& b) { u32x4 w; w.x = cvt_pk_bf16(a[0], a[1]); w.y = cvt_pk_bf16(a[2], a[3]); w.z = cvt_pk_bf16(b[0], b[1]); w.w = cvt_pk_bf16(b[2], b[3]); return w; }
; __device__ __forceinline__ float hsq4(const f32x4& a) { return (a[0] * a[0] + a[1] * a[1]) + (a[2] * a[2] + a[3] * a[3]); }
; #define AT_LAS __attribute__((address_space(3)))
; __device__ __forceinline__ int crow(int r, int hi) { return (r & 3) + 8 * (r >> 2) + 4 * hi; }
; template <int THRL>
; __device__ __forceinline__ void attn_item(int b, int h, int s, const bf16_t* Q, const bf16_t* KN, const bf16_t* KR, const bf16_t* V, const float* goa  , bf16_t* Y, float* ssqy, AT_LAS char* shm, int wid0) {
;     ...
;         { auto rr = __builtin_amdgcn_permlane32_swap(__float_as_uint(l_reg), __float_as_uint(l_reg), false, false); l_reg = __uint_as_float(rr[0]) + __uint_as_float(rr[1]); }
;         if (hi == 0) wsf[32 + r32] = __builtin_amdgcn_rcpf(l_reg);
;         asm volatile("s_waitcnt lgkmcnt(0)" ::: "memory");
;         AT_LAS char* stg = shm + LDS_OST + wid * (32 * OROW);
;         { const int row = lane >> 1, half = lane & 1; const size_t grow = rowbase + q0 + wid * 32 + row; float ss = 0.f;
; #pragma unroll
;           for (int d0 = 0; d0 < 2; ++d0) {
; #pragma unroll
;             for (int r = 0; r < 16; ++r) { const int orow = crow(r, hi); *(AT_LAS float*)(stg + orow * OROW + r32 * 4) = o[d0][r] * wsf[32 + orow]; }
;             asm volatile("s_waitcnt lgkmcnt(0)" ::: "memory");
;             const float* gp = goa + h * 64 + d0 * 32 + half * 16; bf16_t* yp = Y + grow * YLD + 512 + h * 64 + d0 * 32 + half * 16;
; #pragma unroll
;             for (int i = 0; i < 2; ++i) { const f32x4 a = *(AT_LAS const f32x4*)(stg + row * OROW + half * 64 + i * 32), c = *(AT_LAS const f32x4*)(stg + row * OROW + half * 64 + i * 32 + 16);
;                 ss += pg8::hsq4(a) + pg8::hsq4(c);
;                 *(u32x4*)(yp + i * 8) = pg8::pack8(a * *(const f32x4*)(gp + i * 8), c * *(const f32x4*)(gp + i * 8 + 4)); }
;             asm volatile("s_waitcnt lgkmcnt(0)" ::: "memory"); }
;           ss += swz_xor1(ss); if (half == 0) ssqy[grow * 16 + 8 + h] = ss; }
.LBB13_791:
	s_or_b64 exec, exec, s[76:77]
	s_mov_b32 s5, s85
	v_lshl_add_u64 v[18:19], v[140:141], 0, s[4:5]
	v_lshlrev_b64 v[20:21], 12, v[18:19]
	v_lshl_add_u64 v[20:21], v[150:151], 0, v[20:21]
	s_waitcnt lgkmcnt(0)
	ds_read_b128 v[154:157], v194 offset:128
	ds_read_b128 v[158:161], v194 offset:160
	ds_read_b128 v[162:165], v194 offset:192
	ds_read_b128 v[166:169], v194 offset:224
	s_waitcnt lgkmcnt(0)
	v_mul_f32_e32 v170, v50, v154
	v_mul_f32_e32 v171, v51, v155
	v_mul_f32_e32 v172, v52, v156
	v_mul_f32_e32 v173, v53, v157
	v_mul_f32_e32 v174, v54, v158
	v_mul_f32_e32 v175, v55, v159
	v_mul_f32_e32 v176, v56, v160
	v_mul_f32_e32 v177, v57, v161
	v_mul_f32_e32 v178, v58, v162
	v_mul_f32_e32 v179, v59, v163
	v_mul_f32_e32 v180, v60, v164
	v_mul_f32_e32 v181, v61, v165
	v_mul_f32_e32 v198, v62, v166
	v_mul_f32_e32 v199, v63, v167
	v_mul_f32_e32 v200, v64, v168
	v_mul_f32_e32 v201, v65, v169
	ds_write_b32 v195, v170
	ds_write_b32 v196, v171
	ds_write_b32 v196, v172 offset:144
	ds_write_b32 v196, v173 offset:288
	ds_write_b32 v196, v174 offset:1008
	ds_write_b32 v196, v175 offset:1152
	ds_write_b32 v196, v176 offset:1296
	ds_write_b32 v196, v177 offset:1440
	ds_write_b32 v196, v178 offset:2160
	ds_write_b32 v196, v179 offset:2304
	ds_write_b32 v196, v180 offset:2448
	ds_write_b32 v196, v181 offset:2592
	ds_write_b32 v196, v198 offset:3312
	ds_write_b32 v196, v199 offset:3456
	ds_write_b32 v196, v200 offset:3600
	ds_write_b32 v196, v201 offset:3744
	s_waitcnt lgkmcnt(0)
	ds_read_b128 v[22:25], v197
	ds_read_b128 v[26:29], v197 offset:16
	ds_read_b128 v[30:33], v197 offset:32
	ds_read_b128 v[34:37], v197 offset:48
	s_waitcnt lgkmcnt(3)
	v_mul_f32_e32 v0, v23, v23
	v_mul_f32_e32 v39, v25, v25
	v_fmac_f32_e32 v0, v22, v22
	v_fmac_f32_e32 v39, v24, v24
	v_add_f32_e32 v0, v0, v39
	s_waitcnt lgkmcnt(2)
	v_mul_f32_e32 v39, v27, v27
	v_mul_f32_e32 v40, v29, v29
	v_fmac_f32_e32 v39, v26, v26
	v_fmac_f32_e32 v40, v28, v28
	v_add_f32_e32 v39, v39, v40
	v_add_f32_e32 v0, v0, v39
	s_waitcnt vmcnt(15)
	v_pk_mul_f32 v[28:29], v[28:29], v[218:219]
	v_pk_mul_f32 v[24:25], v[24:25], v[222:223]
	v_pk_mul_f32 v[22:23], v[22:23], v[220:221]
	v_pk_mul_f32 v[26:27], v[26:27], v[216:217]
	v_cvt_pk_bf16_f32 v22, v22, v23
	v_cvt_pk_bf16_f32 v23, v24, v25
	s_nop 0
	v_cvt_pk_bf16_f32 v24, v26, v27
	v_cvt_pk_bf16_f32 v25, v28, v29
	global_store_dwordx4 v[20:21], v[22:25], off offset:1024
	s_waitcnt lgkmcnt(1)
	v_mul_f32_e32 v38, v31, v31
	v_mul_f32_e32 v39, v33, v33
	v_fmac_f32_e32 v38, v30, v30
	v_fmac_f32_e32 v39, v32, v32
	v_add_f32_e32 v38, v38, v39
	s_waitcnt lgkmcnt(0)
	v_mul_f32_e32 v39, v35, v35
	v_mul_f32_e32 v40, v37, v37
	v_fmac_f32_e32 v39, v34, v34
	v_fmac_f32_e32 v40, v36, v36
	v_add_f32_e32 v39, v39, v40
	v_add_f32_e32 v38, v38, v39
	v_add_f32_e32 v0, v0, v38
	v_pk_mul_f32 v[36:37], v[36:37], v[226:227]
	v_pk_mul_f32 v[32:33], v[32:33], v[230:231]
	v_pk_mul_f32 v[30:31], v[30:31], v[228:229]
	v_pk_mul_f32 v[34:35], v[34:35], v[224:225]
	v_cvt_pk_bf16_f32 v30, v30, v31
	v_cvt_pk_bf16_f32 v31, v32, v33
	s_nop 0
	v_cvt_pk_bf16_f32 v32, v34, v35
	v_cvt_pk_bf16_f32 v33, v36, v37
	global_store_dwordx4 v[20:21], v[30:33], off offset:1040
	v_mul_f32_e32 v170, v2, v154
	v_mul_f32_e32 v171, v3, v155
	v_mul_f32_e32 v172, v4, v156
	v_mul_f32_e32 v173, v5, v157
	v_mul_f32_e32 v174, v6, v158
	v_mul_f32_e32 v175, v7, v159
	v_mul_f32_e32 v176, v8, v160
	v_mul_f32_e32 v177, v9, v161
	v_mul_f32_e32 v178, v10, v162
	v_mul_f32_e32 v179, v11, v163
	v_mul_f32_e32 v180, v12, v164
	v_mul_f32_e32 v181, v13, v165
	v_mul_f32_e32 v198, v14, v166
	v_mul_f32_e32 v199, v15, v167
	v_mul_f32_e32 v200, v16, v168
	v_mul_f32_e32 v201, v17, v169
	ds_write_b32 v195, v170
	ds_write_b32 v196, v171
	ds_write_b32 v196, v172 offset:144
	ds_write_b32 v196, v173 offset:288
	ds_write_b32 v196, v174 offset:1008
	ds_write_b32 v196, v175 offset:1152
	ds_write_b32 v196, v176 offset:1296
	ds_write_b32 v196, v177 offset:1440
	ds_write_b32 v196, v178 offset:2160
	ds_write_b32 v196, v179 offset:2304
	ds_write_b32 v196, v180 offset:2448
	ds_write_b32 v196, v181 offset:2592
	ds_write_b32 v196, v198 offset:3312
	ds_write_b32 v196, v199 offset:3456
	ds_write_b32 v196, v200 offset:3600
	ds_write_b32 v196, v201 offset:3744
	s_waitcnt lgkmcnt(0)
	ds_read_b128 v[22:25], v197
	ds_read_b128 v[26:29], v197 offset:16
	ds_read_b128 v[30:33], v197 offset:32
	ds_read_b128 v[34:37], v197 offset:48
	s_waitcnt lgkmcnt(3)
	v_mul_f32_e32 v38, v23, v23
	v_mul_f32_e32 v39, v25, v25
	v_fmac_f32_e32 v38, v22, v22
	v_fmac_f32_e32 v39, v24, v24
	v_add_f32_e32 v38, v38, v39
	s_waitcnt lgkmcnt(2)
	v_mul_f32_e32 v39, v27, v27
	v_mul_f32_e32 v40, v29, v29
	v_fmac_f32_e32 v39, v26, v26
	v_fmac_f32_e32 v40, v28, v28
	v_add_f32_e32 v39, v39, v40
	v_add_f32_e32 v38, v38, v39
	v_add_f32_e32 v0, v0, v38
	v_pk_mul_f32 v[28:29], v[28:29], v[234:235]
	v_pk_mul_f32 v[24:25], v[24:25], v[242:243]
	v_pk_mul_f32 v[22:23], v[22:23], v[240:241]
	v_pk_mul_f32 v[26:27], v[26:27], v[232:233]
	v_cvt_pk_bf16_f32 v22, v22, v23
	v_cvt_pk_bf16_f32 v23, v24, v25
	s_nop 0
	v_cvt_pk_bf16_f32 v24, v26, v27
	v_cvt_pk_bf16_f32 v25, v28, v29
	global_store_dwordx4 v[20:21], v[22:25], off offset:1088
	s_waitcnt lgkmcnt(1)
	v_mul_f32_e32 v38, v31, v31
	v_mul_f32_e32 v39, v33, v33
	v_fmac_f32_e32 v38, v30, v30
	v_fmac_f32_e32 v39, v32, v32
	v_add_f32_e32 v38, v38, v39
	s_waitcnt lgkmcnt(0)
	v_mul_f32_e32 v39, v35, v35
	v_mul_f32_e32 v40, v37, v37
	v_fmac_f32_e32 v39, v34, v34
	v_fmac_f32_e32 v40, v36, v36
	v_add_f32_e32 v39, v39, v40
	v_add_f32_e32 v38, v38, v39
	v_add_f32_e32 v0, v0, v38
	v_pk_mul_f32 v[36:37], v[36:37], v[246:247]
	v_pk_mul_f32 v[32:33], v[32:33], v[250:251]
	v_pk_mul_f32 v[30:31], v[30:31], v[248:249]
	v_pk_mul_f32 v[34:35], v[34:35], v[244:245]
	v_cvt_pk_bf16_f32 v30, v30, v31
	v_cvt_pk_bf16_f32 v31, v32, v33
	s_nop 0
	v_cvt_pk_bf16_f32 v32, v34, v35
	v_cvt_pk_bf16_f32 v33, v36, v37
	global_store_dwordx4 v[20:21], v[30:33], off offset:1104
	ds_swizzle_b32 v2, v0 offset:swizzle(SWAP,1)
	s_waitcnt lgkmcnt(0)
	s_mov_b64 s[4:5], exec
	v_readlane_b32 s76, v238, 62
	v_readlane_b32 s77, v238, 63
	s_and_b64 s[76:77], s[4:5], s[76:77]
	s_mov_b64 exec, s[76:77]
	s_cbranch_execz .LBB13_747
	v_readlane_b32 s76, v237, 0
	s_waitcnt lgkmcnt(0)
	v_add_f32_e32 v0, v0, v2
	v_lshlrev_b64 v[2:3], 6, v[18:19]
	v_readlane_b32 s77, v237, 1
	s_nop 1
	v_lshl_add_u64 v[2:3], s[76:77], 0, v[2:3]
	v_add_co_u32_e32 v2, vcc, 0xc00000, v2
	s_nop 1
	v_addc_co_u32_e32 v3, vcc, 0, v3, vcc
	global_store_dword v[2:3], v0, off offset:32
	s_branch .LBB13_747
.Lat0_lastu:
	s_waitcnt vmcnt(0)
	s_branch .LBB13_789

; __device__ __forceinline__ int lane_id() { int l; asm volatile("v_mbcnt_lo_u32_b32 %0, -1, 0\n\tv_mbcnt_hi_u32_b32 %0, -1, %0" : "=v"(l)); return l; }
; #define AT_LAS __attribute__((address_space(3)))
; #define AT_QLOAD(dst, qb_) do { const bf16_t* Qw_ = Q + (rowbase + (qb_) * 256 + wid * 32) * 768 + h * 96; \
;         _Pragma("unroll") for (int d0 = 0; d0 < 6; ++d0) dst[d0] = *(const bf16x8*)(Qw_ + (size_t)r32 * 768 + d0 * 16 + hi * 8); } while (0)
; template <int THRL>
; __device__ __forceinline__ void attn_item(int b, int h, int s, const bf16_t* Q, const bf16_t* KN, const bf16_t* KR, const bf16_t* V, const float* goa  , bf16_t* Y, float* ssqy, AT_LAS char* shm, int wid0) {
;     int tid_ = wid0 * 64 + lane_id(); asm volatile("" : "+v"(tid_));
;     const int tid = tid_, lane = tid & 63, r32 = lane & 31, hi = lane >> 5; const int wid = __builtin_amdgcn_readfirstlane(tid >> 6);
;     const bool late = wid >= 4;
;     const size_t rowbase = (size_t)b * SEQ;
;     const unsigned lds0 = (unsigned)(uintptr_t)shm;
;     AT_LAS float* wsf = (AT_LAS float*)(shm + LDS_WS) + wid * 64;
;     const bf16_t* ksrc = KN + (rowbase + lane) * 512 + h * 64 + wid * 8;
;     const bf16_t* rsrc = KR + (rowbase + lane) * 32 + (wid & 3) * 8;
;     const bf16_t* vsrc = V + (rowbase + 16 * (wid & 3) + (lane >> 2)) * 512 + h * 64 + (wid >> 2) * 32 + (lane & 3) * 8;
;     const unsigned kdst = lds0 + wid * 1024, rdst = lds0 + (8 + (wid & 3)) * 1024, vdst = lds0 + LDS_V + wid * 1024;
;     ...
;     AT_LAS const char* kp0 = shm + hi * 1024 + r32 * 16;
;     AT_LAS const char* vp0 = shm + LDS_V + ((lane >> 4) & 1) * 32 + (lane & 3) * 8 + (4 * hi + ((lane & 15) >> 2)) * 64;
;     const int qrel = wid * 32 + r32, wq = wid >> 1;
;     bf16x8 qr[6];
;     AT_QLOAD(qr, s);
;     { const int NT0 = 4 * s + 4; AT_DMA(0, 0, NT0); AT_DMA(1, 1, NT0); AT_DMA(2, 1, NT0); }
.LBB13_1724:
	s_ashr_i32 s0, s13, 1
	v_readlane_b32 s1, v238, 48
	s_add_i32 s1, s0, s1
	v_writelane_b32 v238, s13, 49
	s_ashr_i32 s0, s1, 3
	s_and_b32 s3, s1, 7
	v_readlane_b32 s1, v238, 2
	v_mbcnt_lo_u32_b32 v0, -1, 0
	v_mbcnt_hi_u32_b32 v0, -1, v0
	v_readlane_b32 s8, v238, 44
	v_readlane_b32 s9, v238, 45
	v_add_u32_e32 v12, s1, v0
	s_ashr_i32 s1, s0, 31
	v_readfirstlane_b32 s10, v12
	s_ashr_i32 s11, s10, 6
	s_and_b32 s2, s11, 3
	v_and_b32_e32 v13, 63, v12
	s_lshl_b64 s[0:1], s[0:1], 11
	s_lshl_b32 s6, s2, 4
	v_bfe_u32 v0, v12, 2, 4
	s_waitcnt lgkmcnt(0)
	v_or_b32_e32 v2, s0, v13
	v_mov_b32_e32 v3, s1
	v_or_b32_e32 v0, s6, v0
	v_lshlrev_b64 v[4:5], 10, v[2:3]
	v_lshlrev_b64 v[6:7], 6, v[2:3]
	v_or_b32_e32 v2, s0, v0
	v_lshlrev_b64 v[2:3], 10, v[2:3]
	v_lshl_add_u64 v[2:3], s[8:9], 0, v[2:3]
	s_ashr_i32 s8, s10, 3
	s_lshl_b32 s2, s2, 10
	s_and_b32 s17, s13, 1
	s_lshl_b32 s4, s11, 3
	s_andn2_b32 s8, s8, 31
	s_or_b32 s19, s2, 0x2000
	s_lshl_b32 s12, s11, 5
	s_and_b32 s7, s10, 0x3fffffc0
	s_ashr_i32 s5, s4, 31
	s_ashr_i32 s9, s8, 31
	s_lshl_b32 s18, s11, 10
	s_add_i32 s2, s19, 0
	s_lshl_b32 s13, s17, 8
	s_ashr_i32 s14, s12, 31
	s_add_u32 s20, s0, s12
	s_addc_u32 s21, s1, s14
	s_add_u32 s0, s20, s13
	v_and_b32_e32 v14, 31, v12
	v_lshlrev_b32_e32 v0, 3, v12
	s_addc_u32 s1, s21, 0
	v_and_b32_e32 v16, 24, v0
	v_lshlrev_b32_e32 v0, 1, v12
	v_or_b32_e32 v22, s12, v14
	s_mulk_i32 s1, 0x600
	s_mul_hi_u32 s12, s0, 0x600
	v_bfe_u32 v15, v12, 5, 1
	v_and_b32_e32 v0, 32, v0
	s_add_i32 s12, s12, s1
	s_mulk_i32 s0, 0x600
	v_readlane_b32 s13, v238, 38
	v_add_u32_e32 v19, 0, v0
	v_lshlrev_b32_e32 v20, 2, v15
	v_lshrrev_b32_e32 v0, 2, v12
	s_add_u32 s0, s13, s0
	v_readlane_b32 s16, v238, 39
	v_and_or_b32 v0, v0, 3, v20
	s_addc_u32 s1, s16, s12
	s_mul_i32 s12, s3, 0xc0
	v_lshlrev_b32_e32 v21, 6, v0
	s_add_u32 s0, s0, s12
	v_mul_u32_u24_e32 v0, 0x300, v14
	s_addc_u32 s1, s1, 0
	v_lshlrev_b32_e32 v0, 1, v0
	v_lshl_add_u64 v[8:9], s[0:1], 0, v[0:1]
	v_lshlrev_b32_e32 v10, 4, v15
	v_mov_b32_e32 v11, v1
	v_lshl_add_u64 v[8:9], v[8:9], 0, v[10:11]
	global_load_dwordx4 v[82:85], v[8:9], off
	global_load_dwordx4 v[86:89], v[8:9], off offset:32
	global_load_dwordx4 v[90:93], v[8:9], off offset:64
	global_load_dwordx4 v[94:97], v[8:9], off offset:96
	global_load_dwordx4 v[98:101], v[8:9], off offset:128
	global_load_dwordx4 v[102:105], v[8:9], off offset:160
	s_cmp_gt_i32 s11, 3
	v_readlane_b32 s14, v238, 40
	s_cselect_b64 s[90:91], -1, 0
	s_cmp_lt_i32 s11, 4
	v_readlane_b32 s15, v238, 41
	s_cselect_b64 s[0:1], -1, 0
	s_lshl_b32 s84, s3, 7
	v_lshl_add_u64 v[4:5], s[14:15], 0, v[4:5]
	v_lshl_add_u64 v[4:5], v[4:5], 0, s[84:85]
	s_lshl_b32 s7, s7, 2
	v_lshl_add_u64 v[122:123], s[4:5], 1, v[4:5]
	v_lshrrev_b32_e32 v214, 3, v13
	v_lshl_add_u32 v214, s11, 3, v214
	v_sub_u32_e32 v214, v214, v13
	v_lshlrev_b32_e32 v214, 10, v214
	v_lshrrev_b32_e32 v215, 4, v13
	v_lshl_add_u32 v215, s11, 2, v215
	v_xor_b32_e32 v215, v215, v13
	v_and_b32_e32 v215, 7, v215
	v_subrev_u32_e32 v215, s11, v215
	v_lshl_add_u32 v214, v215, 4, v214
	v_ashrrev_i32_e32 v215, 31, v214
	v_lshl_add_u64 v[122:123], v[122:123], 0, v[214:215]
	v_readlane_b32 s4, v238, 42
	s_add_i32 s7, s7, 0
	v_readlane_b32 s5, v238, 43
	s_add_i32 s76, s7, 0x14000
	s_mov_b32 s7, s85
	v_lshl_add_u64 v[4:5], s[4:5], 0, v[6:7]
	v_lshl_add_u64 v[2:3], v[2:3], 0, s[84:85]
	s_add_i32 s87, s18, 0
	s_mov_b32 s4, m0
	s_mov_b32 m0, s87
	s_nop 0
	global_load_lds_dwordx4 v[122:123], off
	s_mov_b32 m0, s4
	v_lshl_add_u64 v[124:125], v[4:5], 0, s[6:7]
	v_lshl_add_u64 v[2:3], s[8:9], 1, v[2:3]
	v_lshlrev_b32_e32 v4, 1, v16
	v_mov_b32_e32 v5, v1
	s_mov_b32 s4, m0
	s_mov_b32 m0, s2
	s_nop 0
	global_load_lds_dwordx4 v[124:125], off
	s_mov_b32 m0, s4
	v_lshl_add_u64 v[126:127], v[2:3], 0, v[4:5]
	s_add_i32 s78, s87, 0xc000
	s_mov_b32 s4, m0
	s_mov_b32 m0, s78
	s_nop 0
	global_load_lds_dwordx4 v[126:127], off
	s_mov_b32 m0, s4
	s_mov_b64 s[8:9], 0x10000
	v_readlane_b32 s6, v238, 14
	v_lshl_add_u64 v[128:129], v[122:123], 0, s[8:9]
	s_add_i32 s5, s18, s6
	s_mov_b32 s4, m0
	s_mov_b32 m0, s5
	s_nop 0
	global_load_lds_dwordx4 v[128:129], off
	s_mov_b32 m0, s4
	v_writelane_b32 v238, s5, 50
	s_mov_b64 s[4:5], 0x1000
	v_lshl_add_u64 v[130:131], v[124:125], 0, s[4:5]
	s_add_i32 s5, s19, s6
	v_writelane_b32 v238, s5, 51
	s_mov_b32 s4, m0
	s_mov_b32 m0, s5
	s_nop 0
	global_load_lds_dwordx4 v[130:131], off
	s_mov_b32 m0, s4
	v_lshl_add_u64 v[132:133], v[126:127], 0, s[8:9]
	s_add_i32 s7, s87, 0xe000
	s_mov_b32 s4, m0
	s_mov_b32 m0, s7
	s_nop 0
	global_load_lds_dwordx4 v[132:133], off
	s_mov_b32 m0, s4
	s_mov_b64 s[14:15], 0x20000
	v_readlane_b32 s6, v238, 15
	v_lshl_add_u64 v[134:135], v[122:123], 0, s[14:15]
	v_writelane_b32 v238, s18, 52
	s_add_i32 s5, s18, s6
	s_mov_b32 s4, m0
	s_mov_b32 m0, s5
	s_nop 0
	global_load_lds_dwordx4 v[134:135], off
	s_mov_b32 m0, s4
; #define AT_LAS __attribute__((address_space(3)))
; #define AT_WAIT_BAR(N) asm volatile("s_waitcnt vmcnt(" #N ") lgkmcnt(0)\n\ts_barrier" ::: "memory")
; #define AT_QLOAD(dst, qb_) do { const bf16_t* Qw_ = Q + (rowbase + (qb_) * 256 + wid * 32) * 768 + h * 96; \
;         _Pragma("unroll") for (int d0 = 0; d0 < 6; ++d0) dst[d0] = *(const bf16x8*)(Qw_ + (size_t)r32 * 768 + d0 * 16 + hi * 8); } while (0)
; template <int THRL>
; __device__ __forceinline__ void attn_item(int b, int h, int s, const bf16_t* Q, const bf16_t* KN, const bf16_t* KR, const bf16_t* V, const float* goa  , bf16_t* Y, float* ssqy, AT_LAS char* shm, int wid0) {
;     ...
;     AT_LAS const char* kp0 = shm + hi * 1024 + r32 * 16;
;     AT_LAS const char* vp0 = shm + LDS_V + ((lane >> 4) & 1) * 32 + (lane & 3) * 8 + (4 * hi + ((lane & 15) >> 2)) * 64;
;     const int qrel = wid * 32 + r32, wq = wid >> 1;
;     bf16x8 qr[6];
;     AT_QLOAD(qr, s);
;     { const int NT0 = 4 * s + 4; AT_DMA(0, 0, NT0); AT_DMA(1, 1, NT0); AT_DMA(2, 1, NT0); }
;     for (int ui = 0; ui < 4; ++ui) {
;         const int qb = (ui == 0) ? s : (ui == 1) ? 7 - s : (ui == 2) ? 2 + s : 5 - s; const int q0 = qb * 256;
;         const int NT = (q0 + 256) / KVBLK;
;         float mhat = 0.f, l_reg = 0.f; f32x16 o[2]; o[0] = f32x16{}; o[1] = f32x16{};
;         f32x16 negm = f32x16{}; asm volatile("" : "+v"(negm));
;         u32x4 pw0 = u32x4{}, pw1 = u32x4{}, pw2 = u32x4{}, pw3 = u32x4{}; bool have = false;
;         f32x16 p0 = f32x16{}, p1 = f32x16{};
;         AT_WAIT_BAR(6);
;         if (!late) qkt(p0, p1, kp0, qr, negm);
;         for (int t = 0; t < NT; ++t) {
;             AT_WAIT_BAR(3);
;             AT_DMA(t + 3, t + 2, NT);
;             const int jb = t - (NT - 4);
;             const bool need = jb <= wq;
;             if (late) { if (have) pv(o, vp0 + ((t - 1) & 3) * VSLOTB, pw0, pw1, pw2, pw3);
;                         have = false; if (need) qkt(p0, p1, kp0 + (t & 3) * KSLOTB, qr, negm); }
;             if (need) {
;                 if (jb == wq) { const int kb = 64 * jb + 4 * hi;
; #pragma unroll
;                     for (int r = 0; r < 16; ++r) { const int kv = kb + (r & 3) + 8 * (r >> 2); if (kv > qrel) p0[r] = -INFINITY; if (kv + 32 > qrel) p1[r] = -INFINITY; } }
	v_writelane_b32 v238, s5, 53
	s_mov_b64 s[4:5], 0x2000
	v_lshl_add_u64 v[136:137], v[124:125], 0, s[4:5]
	s_add_i32 s5, s19, s6
	s_mov_b32 s4, m0
	s_mov_b32 m0, s5
	s_nop 0
	global_load_lds_dwordx4 v[136:137], off
	s_mov_b32 m0, s4
	s_ashr_i32 s33, s10, 7
	v_writelane_b32 v238, s19, 54
	s_mov_b32 s4, m0
	s_mov_b32 m0, s7
	s_nop 0
	global_load_lds_dwordx4 v[132:133], off
	s_mov_b32 m0, s4
	v_writelane_b32 v238, s5, 55
	s_add_u32 s4, s13, s12
	v_writelane_b32 v238, s7, 56
	s_addc_u32 s5, s16, 0
	s_or_b32 s6, s17, 2
	v_writelane_b32 v238, s6, 57
	v_writelane_b32 v238, s17, 58
	s_xor_b32 s6, s17, 7
	v_writelane_b32 v238, s6, 59
	s_mulk_i32 s11, 0x1200
	v_writelane_b32 v238, s20, 60
	v_lshl_add_u64 v[2:3], s[4:5], 0, v[0:1]
	s_add_i32 s4, s11, 0
	v_writelane_b32 v238, s21, 61
	s_xor_b32 s86, s17, 5
	s_add_i32 s8, s4, 0x14800
	s_lshl_b32 s4, s3, 8
	v_readlane_b32 s10, v238, 46
	v_lshl_add_u64 v[138:139], v[2:3], 0, v[10:11]
	v_and_b32_e32 v3, 1, v12
	v_readlane_b32 s11, v238, 47
	s_add_u32 s4, s10, s4
	s_addc_u32 s5, s11, 0
	v_lshlrev_b32_e32 v0, 6, v3
	v_bfe_u32 v2, v12, 1, 5
	v_lshl_add_u64 v[142:143], s[4:5], 0, v[0:1]
	v_mov_b32_e32 v5, s8
	s_movk_i32 s4, 0x90
	v_or_b32_e32 v140, s20, v2
	v_mad_u32_u24 v5, v2, s4, v5
	v_lshl_or_b32 v2, s33, 6, v20
	v_or_b32_e32 v6, 32, v2
	v_cmp_gt_i32_e64 s[12:13], v6, v22
	v_or_b32_e32 v6, 33, v2
	v_cmp_gt_i32_e64 s[16:17], v6, v22
	v_or_b32_e32 v6, 2, v2
	v_cmp_gt_i32_e64 s[18:19], v6, v22
	v_or_b32_e32 v6, 34, v2
	v_mov_b32_e32 v141, s21
	v_cmp_gt_i32_e64 s[20:21], v6, v22
	v_or_b32_e32 v6, 3, v2
	v_cmp_gt_i32_e64 s[22:23], v6, v22
	v_or_b32_e32 v6, 35, v2
	v_cmp_gt_i32_e64 s[24:25], v6, v22
	v_or_b32_e32 v6, 8, v2
	v_cmp_gt_i32_e64 s[26:27], v6, v22
	v_or_b32_e32 v6, 40, v2
	v_cmp_gt_i32_e64 s[28:29], v6, v22
	v_or_b32_e32 v6, 9, v2
	v_cmp_gt_i32_e64 s[30:31], v6, v22
	v_or_b32_e32 v6, 41, v2
	v_cmp_gt_i32_e64 s[34:35], v6, v22
	v_or_b32_e32 v6, 10, v2
	v_cmp_gt_i32_e64 s[36:37], v6, v22
	v_or_b32_e32 v6, 42, v2
	v_cmp_gt_i32_e64 s[38:39], v6, v22
	v_or_b32_e32 v6, 11, v2
	v_cmp_gt_i32_e64 s[40:41], v6, v22
	v_or_b32_e32 v6, 43, v2
	v_cmp_gt_i32_e64 s[42:43], v6, v22
	v_or_b32_e32 v6, 16, v2
	v_cmp_gt_i32_e64 s[44:45], v6, v22
	v_or_b32_e32 v6, 48, v2
	v_cmp_gt_i32_e64 s[46:47], v6, v22
	v_or_b32_e32 v6, 17, v2
	v_cmp_gt_i32_e64 s[48:49], v6, v22
	v_or_b32_e32 v6, 49, v2
	v_cmp_gt_i32_e64 s[50:51], v6, v22
	v_or_b32_e32 v6, 18, v2
	v_cmp_gt_i32_e64 s[52:53], v6, v22
	v_or_b32_e32 v6, 50, v2
	v_cmp_eq_u32_e64 s[4:5], 0, v3
	v_cmp_gt_i32_e64 s[54:55], v6, v22
	v_or_b32_e32 v6, 19, v2
	v_writelane_b32 v238, s4, 62
	v_cmp_gt_i32_e64 s[56:57], v6, v22
	v_or_b32_e32 v6, 51, v2
	v_writelane_b32 v238, s5, 63
	v_cmp_gt_i32_e64 s[58:59], v6, v22
	v_or_b32_e32 v6, 24, v2
	s_lshl_b32 s3, s3, 2
	v_readlane_b32 s4, v238, 36
	v_cmp_gt_i32_e64 s[60:61], v6, v22
	v_or_b32_e32 v6, 56, v2
	s_add_u32 s4, s4, s3
	v_readlane_b32 s3, v238, 37
	v_cmp_gt_i32_e64 s[62:63], v6, v22
	v_or_b32_e32 v6, 25, v2
	s_addc_u32 s5, s3, 0
	v_cmp_gt_i32_e64 s[64:65], v6, v22
	v_or_b32_e32 v6, 57, v2
	v_writelane_b32 v237, s4, 0
	v_cmp_gt_i32_e64 s[66:67], v6, v22
	v_or_b32_e32 v6, 26, v2
	v_writelane_b32 v237, s5, 1
	s_mov_b64 s[4:5], 0x30000
	v_cmp_gt_i32_e64 s[68:69], v6, v22
	v_or_b32_e32 v6, 58, v2
	v_lshl_add_u64 v[144:145], v[122:123], 0, s[4:5]
	s_mov_b64 s[4:5], 0x3000
	v_lshl_add_u64 v[148:149], v[126:127], 0, s[14:15]
	v_cmp_gt_i32_e64 s[10:11], v2, v22
	v_cmp_lt_i32_e64 s[14:15], v2, v22
	v_cmp_gt_i32_e64 s[70:71], v6, v22
	v_or_b32_e32 v6, 27, v2
	v_or_b32_e32 v2, 59, v2
	v_readlane_b32 s3, v238, 34
	v_lshlrev_b32_e32 v4, 2, v14
	v_lshl_add_u64 v[146:147], v[124:125], 0, s[4:5]
	v_cmp_gt_i32_e64 s[74:75], v2, v22
	v_or_b32_e32 v2, 1, v20
	s_add_u32 s4, s3, s84
	v_readlane_b32 s3, v238, 35
	v_lshlrev_b32_e32 v17, 10, v15
	v_lshlrev_b32_e32 v18, 4, v14
	v_lshrrev_b32_e32 v252, 3, v14
	v_lshlrev_b32_e32 v252, 10, v252
	v_and_b32_e32 v253, 7, v14
	v_lshl_add_u32 v252, v253, 7, v252
	v_bfe_u32 v253, v14, 1, 1
	v_xor_b32_e32 v253, v253, v15
	v_lshl_add_u32 v252, v253, 4, v252
	v_bfe_u32 v253, v14, 2, 2
	v_lshl_add_u32 v252, v253, 5, v252
	v_xor_b32_e32 v253, 32, v252
	v_xor_b32_e32 v254, 64, v252
	v_xor_b32_e32 v255, 0x60, v252
	v_add3_u32 v191, v19, v16, v21
	v_add_u32_e32 v193, s76, v4
	v_add_u32_e32 v4, s8, v4
	v_cmp_gt_i32_e64 s[72:73], v6, v22
	v_mul_u32_u24_e32 v6, 0x240, v15
	v_mul_u32_u24_e32 v7, 0x90, v2
	s_addc_u32 s5, s3, 0
	v_lshlrev_b32_e32 v2, 5, v3
	v_mov_b32_e32 v3, v1
	v_add3_u32 v190, 0, v17, v18
	v_add_u32_e32 v192, 0xc000, v191
	v_cmp_gt_u32_e64 s[6:7], 32, v13
	s_mov_b32 s8, 0
	v_add_u32_e32 v194, s76, v10
	v_lshl_add_u64 v[150:151], s[4:5], 0, v[2:3]
	s_sub_i32 s3, 0, s33
	v_add_u32_e32 v195, v4, v6
	v_add_u32_e32 v196, v4, v7
	v_add_u32_e32 v197, v5, v0
	v_writelane_b32 v237, s3, 2
	s_branch .LBB13_1726

; #define AT_LAS __attribute__((address_space(3)))
; #define AT_WAIT_BAR(N) asm volatile("s_waitcnt vmcnt(" #N ") lgkmcnt(0)\n\ts_barrier" ::: "memory")
; __device__ __forceinline__ void qkt(f32x16& p0, f32x16& p1, AT_LAS const char* kb, const bf16x8 (&qr)[6], const f32x16& negm) {
;     bf16x8 kf[12];
; #pragma unroll
;     for (int d0 = 0; d0 < 6; ++d0) { kf[2 * d0] = *(AT_LAS const bf16x8*)(kb + d0 * 2048); kf[2 * d0 + 1] = *(AT_LAS const bf16x8*)(kb + d0 * 2048 + 512); }
;     __builtin_amdgcn_sched_barrier(0);
;     p0 = __builtin_amdgcn_mfma_f32_32x32x16_bf16(kf[0], qr[0], negm, 0, 0, 0); p1 = __builtin_amdgcn_mfma_f32_32x32x16_bf16(kf[1], qr[0], negm, 0, 0, 0);
; #pragma unroll
;     for (int d0 = 1; d0 < 6; ++d0) { p0 = __builtin_amdgcn_mfma_f32_32x32x16_bf16(kf[2 * d0], qr[d0], p0, 0, 0, 0); p1 = __builtin_amdgcn_mfma_f32_32x32x16_bf16(kf[2 * d0 + 1], qr[d0], p1, 0, 0, 0); }
;     asm volatile("s_nop 15\n\ts_nop 7" : "+v"(p0), "+v"(p1));
; }
; template <int THRL>
; __device__ __forceinline__ void attn_item(int b, int h, int s, const bf16_t* Q, const bf16_t* KN, const bf16_t* KR, const bf16_t* V, const float* goa  , bf16_t* Y, float* ssqy, AT_LAS char* shm, int wid0) {
;     ...
;     for (int ui = 0; ui < 4; ++ui) {
;         const int qb = (ui == 0) ? s : (ui == 1) ? 7 - s : (ui == 2) ? 2 + s : 5 - s; const int q0 = qb * 256;
;         const int NT = (q0 + 256) / KVBLK;
;         float mhat = 0.f, l_reg = 0.f; f32x16 o[2]; o[0] = f32x16{}; o[1] = f32x16{};
;         f32x16 negm = f32x16{}; asm volatile("" : "+v"(negm));
;         u32x4 pw0 = u32x4{}, pw1 = u32x4{}, pw2 = u32x4{}, pw3 = u32x4{}; bool have = false;
;         f32x16 p0 = f32x16{}, p1 = f32x16{};
;         AT_WAIT_BAR(6);
;         if (!late) qkt(p0, p1, kp0, qr, negm);
.LBB13_1726:
	v_mov_b32_e32 v14, v1
	v_mov_b32_e32 v15, v1
	v_mov_b32_e32 v0, v1
	s_waitcnt lgkmcnt(0)
	v_mov_b32_e32 v2, v1
	v_mov_b32_e32 v3, v1
	v_mov_b32_e32 v4, v1
	v_mov_b32_e32 v5, v1
	v_mov_b32_e32 v6, v1
	v_mov_b32_e32 v7, v1
	v_mov_b32_e32 v8, v1
	v_mov_b32_e32 v9, v1
	v_mov_b32_e32 v10, v1
	v_mov_b32_e32 v11, v1
	v_mov_b32_e32 v12, v1
	v_mov_b32_e32 v13, v1
	v_mov_b64_e32 v[80:81], v[14:15]
	v_mov_b64_e32 v[78:79], v[12:13]
	v_mov_b64_e32 v[76:77], v[10:11]
	v_mov_b64_e32 v[74:75], v[8:9]
	v_mov_b64_e32 v[72:73], v[6:7]
	v_mov_b64_e32 v[70:71], v[4:5]
	v_mov_b64_e32 v[68:69], v[2:3]
	v_mov_b64_e32 v[66:67], v[0:1]
	s_waitcnt vmcnt(6) lgkmcnt(0)
	s_barrier
	v_cndmask_b32_e64 v16, 0, 1, s[0:1]
	v_cmp_ne_u32_e64 s[76:77], 1, v16
	s_andn2_b64 vcc, exec, s[0:1]
	s_cbranch_vccnz .LBB13_1728
	ds_read_b128 v[2:5], v252
	ds_read_b128 v[6:9], v252 offset:4096
	ds_read_b128 v[10:13], v253
	ds_read_b128 v[14:17], v253 offset:4096
	ds_read_b128 v[50:53], v254
	ds_read_b128 v[54:57], v254 offset:4096
	ds_read_b128 v[58:61], v255
	ds_read_b128 v[62:65], v255 offset:4096
	ds_read_b128 v[106:109], v190 offset:8192
	ds_read_b128 v[110:113], v190 offset:8704
	ds_read_b128 v[114:117], v190 offset:10240
	ds_read_b128 v[118:121], v190 offset:10752
	s_waitcnt lgkmcnt(11)
	v_mfma_f32_32x32x16_bf16 v[18:33], v[2:5], v[82:85], v[66:81]
	s_waitcnt lgkmcnt(10)
	v_mfma_f32_32x32x16_bf16 v[34:49], v[6:9], v[82:85], v[66:81]
	s_waitcnt lgkmcnt(9)
	v_mfma_f32_32x32x16_bf16 v[18:33], v[10:13], v[86:89], v[18:33]
	s_waitcnt lgkmcnt(8)
	v_mfma_f32_32x32x16_bf16 v[34:49], v[14:17], v[86:89], v[34:49]
	s_waitcnt lgkmcnt(7)
	v_mfma_f32_32x32x16_bf16 v[18:33], v[50:53], v[90:93], v[18:33]
	s_waitcnt lgkmcnt(6)
	v_mfma_f32_32x32x16_bf16 v[34:49], v[54:57], v[90:93], v[34:49]
	s_waitcnt lgkmcnt(5)
	v_mfma_f32_32x32x16_bf16 v[18:33], v[58:61], v[94:97], v[18:33]
	s_waitcnt lgkmcnt(4)
	v_mfma_f32_32x32x16_bf16 v[34:49], v[62:65], v[94:97], v[34:49]
	s_waitcnt lgkmcnt(3)
	v_mfma_f32_32x32x16_bf16 v[18:33], v[106:109], v[98:101], v[18:33]
	s_waitcnt lgkmcnt(2)
	v_mfma_f32_32x32x16_bf16 v[34:49], v[110:113], v[98:101], v[34:49]
	s_waitcnt lgkmcnt(1)
	v_mfma_f32_32x32x16_bf16 v[18:33], v[114:117], v[102:105], v[18:33]
	s_waitcnt lgkmcnt(0)
	v_mfma_f32_32x32x16_bf16 v[34:49], v[118:121], v[102:105], v[34:49]
	s_nop 15
	s_nop 7
	s_branch .LBB13_1729

; #define AT_LAS __attribute__((address_space(3)))
; #define AT_WAIT_BAR(N) asm volatile("s_waitcnt vmcnt(" #N ") lgkmcnt(0)\n\ts_barrier" ::: "memory")
; __device__ __forceinline__ void qkt(f32x16& p0, f32x16& p1, AT_LAS const char* kb, const bf16x8 (&qr)[6], const f32x16& negm) {
;     bf16x8 kf[12];
; #pragma unroll
;     for (int d0 = 0; d0 < 6; ++d0) { kf[2 * d0] = *(AT_LAS const bf16x8*)(kb + d0 * 2048); kf[2 * d0 + 1] = *(AT_LAS const bf16x8*)(kb + d0 * 2048 + 512); }
;     __builtin_amdgcn_sched_barrier(0);
;     p0 = __builtin_amdgcn_mfma_f32_32x32x16_bf16(kf[0], qr[0], negm, 0, 0, 0); p1 = __builtin_amdgcn_mfma_f32_32x32x16_bf16(kf[1], qr[0], negm, 0, 0, 0);
; #pragma unroll
;     for (int d0 = 1; d0 < 6; ++d0) { p0 = __builtin_amdgcn_mfma_f32_32x32x16_bf16(kf[2 * d0], qr[d0], p0, 0, 0, 0); p1 = __builtin_amdgcn_mfma_f32_32x32x16_bf16(kf[2 * d0 + 1], qr[d0], p1, 0, 0, 0); }
;     asm volatile("s_nop 15\n\ts_nop 7" : "+v"(p0), "+v"(p1));
; }
; template <int THRL>
; __device__ __forceinline__ void attn_item(int b, int h, int s, const bf16_t* Q, const bf16_t* KN, const bf16_t* KR, const bf16_t* V, const float* goa  , bf16_t* Y, float* ssqy, AT_LAS char* shm, int wid0) {
;     ...
;         for (int t = 0; t < NT; ++t) {
;             AT_WAIT_BAR(3);
;             AT_DMA(t + 3, t + 2, NT);
;             const int jb = t - (NT - 4);
;             const bool need = jb <= wq;
;             if (late) { if (have) pv(o, vp0 + ((t - 1) & 3) * VSLOTB, pw0, pw1, pw2, pw3);
;                         have = false; if (need) qkt(p0, p1, kp0 + (t & 3) * KSLOTB, qr, negm); }
.LBB13_1729:
	s_cmp_eq_u32 s8, 2
	v_readlane_b32 s3, v238, 57
	s_cselect_b32 s3, s3, s86
	s_cmp_eq_u32 s8, 1
	s_cselect_b64 s[82:83], -1, 0
	s_and_b64 s[4:5], s[82:83], exec
	v_readlane_b32 s4, v238, 59
	s_cselect_b32 s3, s4, s3
	s_cmp_eq_u32 s8, 0
	s_cselect_b64 s[94:95], -1, 0
	s_and_b64 s[4:5], s[94:95], exec
	v_readlane_b32 s4, v238, 58
	v_readlane_b32 s80, v238, 16
	v_readlane_b32 s5, v238, 52
	s_cselect_b32 s9, s4, s3
	s_waitcnt vmcnt(3) lgkmcnt(0)
	s_barrier
	s_add_i32 s5, s5, s80
	s_lshl_b32 s4, s9, 8
	s_mov_b32 s79, m0
	s_mov_b32 m0, s5
	s_nop 0
	global_load_lds_dwordx4 v[144:145], off
	s_mov_b32 m0, s79
	v_readlane_b32 s5, v238, 54
	s_add_i32 s3, s4, 0x100
	s_add_i32 s5, s5, s80
	s_lshr_b32 s3, s3, 6
	s_mov_b32 s79, m0
	s_mov_b32 m0, s5
	s_nop 0
	global_load_lds_dwordx4 v[146:147], off
	s_mov_b32 m0, s79
	s_add_i32 s5, s87, 0x10000
	s_mov_b32 s79, m0
	s_mov_b32 m0, s5
	s_nop 0
	global_load_lds_dwordx4 v[148:149], off
	s_mov_b32 m0, s79
	s_sub_i32 s5, 4, s3
	s_cmp_le_i32 s5, s33
	s_cselect_b64 s[92:93], -1, 0
	s_and_b64 s[80:81], s[90:91], s[92:93]
	s_andn2_b64 vcc, exec, s[80:81]
	s_cbranch_vccnz .LBB13_1731
	ds_read_b128 v[2:5], v252
	ds_read_b128 v[6:9], v252 offset:4096
	ds_read_b128 v[10:13], v253
	ds_read_b128 v[14:17], v253 offset:4096
	ds_read_b128 v[50:53], v254
	ds_read_b128 v[54:57], v254 offset:4096
	ds_read_b128 v[58:61], v255
	ds_read_b128 v[62:65], v255 offset:4096
	ds_read_b128 v[106:109], v190 offset:8192
	ds_read_b128 v[110:113], v190 offset:8704
	ds_read_b128 v[114:117], v190 offset:10240
	ds_read_b128 v[118:121], v190 offset:10752
	s_waitcnt lgkmcnt(11)
	v_mfma_f32_32x32x16_bf16 v[18:33], v[2:5], v[82:85], v[66:81]
	s_waitcnt lgkmcnt(10)
	v_mfma_f32_32x32x16_bf16 v[34:49], v[6:9], v[82:85], v[66:81]
	s_waitcnt lgkmcnt(9)
	v_mfma_f32_32x32x16_bf16 v[18:33], v[10:13], v[86:89], v[18:33]
	s_waitcnt lgkmcnt(8)
	v_mfma_f32_32x32x16_bf16 v[34:49], v[14:17], v[86:89], v[34:49]
	s_waitcnt lgkmcnt(7)
	v_mfma_f32_32x32x16_bf16 v[18:33], v[50:53], v[90:93], v[18:33]
	s_waitcnt lgkmcnt(6)
	v_mfma_f32_32x32x16_bf16 v[34:49], v[54:57], v[90:93], v[34:49]
	s_waitcnt lgkmcnt(5)
	v_mfma_f32_32x32x16_bf16 v[18:33], v[58:61], v[94:97], v[18:33]
	s_waitcnt lgkmcnt(4)
	v_mfma_f32_32x32x16_bf16 v[34:49], v[62:65], v[94:97], v[34:49]
	s_waitcnt lgkmcnt(3)
	v_mfma_f32_32x32x16_bf16 v[18:33], v[106:109], v[98:101], v[18:33]
	s_waitcnt lgkmcnt(2)
	v_mfma_f32_32x32x16_bf16 v[34:49], v[110:113], v[98:101], v[34:49]
	s_waitcnt lgkmcnt(1)
	v_mfma_f32_32x32x16_bf16 v[18:33], v[114:117], v[102:105], v[18:33]
	s_waitcnt lgkmcnt(0)
	v_mfma_f32_32x32x16_bf16 v[34:49], v[118:121], v[102:105], v[34:49]
	s_nop 15
	s_nop 7

; #define AT_LAS __attribute__((address_space(3)))
; __device__ __forceinline__ void qkt(f32x16& p0, f32x16& p1, AT_LAS const char* kb, const bf16x8 (&qr)[6], const f32x16& negm) {
;     bf16x8 kf[12];
; #pragma unroll
;     for (int d0 = 0; d0 < 6; ++d0) { kf[2 * d0] = *(AT_LAS const bf16x8*)(kb + d0 * 2048); kf[2 * d0 + 1] = *(AT_LAS const bf16x8*)(kb + d0 * 2048 + 512); }
;     __builtin_amdgcn_sched_barrier(0);
;     p0 = __builtin_amdgcn_mfma_f32_32x32x16_bf16(kf[0], qr[0], negm, 0, 0, 0); p1 = __builtin_amdgcn_mfma_f32_32x32x16_bf16(kf[1], qr[0], negm, 0, 0, 0);
; #pragma unroll
;     for (int d0 = 1; d0 < 6; ++d0) { p0 = __builtin_amdgcn_mfma_f32_32x32x16_bf16(kf[2 * d0], qr[d0], p0, 0, 0, 0); p1 = __builtin_amdgcn_mfma_f32_32x32x16_bf16(kf[2 * d0 + 1], qr[d0], p1, 0, 0, 0); }
;     asm volatile("s_nop 15\n\ts_nop 7" : "+v"(p0), "+v"(p1));
; }
; template <int THRL>
; __device__ __forceinline__ void attn_item(int b, int h, int s, const bf16_t* Q, const bf16_t* KN, const bf16_t* KR, const bf16_t* V, const float* goa  , bf16_t* Y, float* ssqy, AT_LAS char* shm, int wid0) {
;     ...
;             if (!late) { if (t + 1 < NT && (jb + 1) <= wq) qkt(p0, p1, kp0 + ((t + 1) & 3) * KSLOTB, qr, negm); }
.LBB13_1739:
	s_cmp_ge_i32 s5, s33
	s_cselect_b64 s[80:81], -1, 0
	s_or_b64 s[80:81], s[90:91], s[80:81]
	s_andn2_b64 vcc, exec, s[80:81]
	s_cbranch_vccz .LBB13_1741
	ds_read_b128 v[34:37], v252 offset:12288
	ds_read_b128 v[154:157], v252 offset:16384
	ds_read_b128 v[158:161], v253 offset:12288
	ds_read_b128 v[162:165], v253 offset:16384
	ds_read_b128 v[166:169], v254 offset:12288
	ds_read_b128 v[170:173], v254 offset:16384
	ds_read_b128 v[174:177], v255 offset:12288
	ds_read_b128 v[178:181], v255 offset:16384
	ds_read_b128 v[198:201], v190 offset:20480
	ds_read_b128 v[202:205], v190 offset:20992
	ds_read_b128 v[206:209], v190 offset:22528
	ds_read_b128 v[210:213], v190 offset:23040
	s_waitcnt lgkmcnt(11)
	v_mfma_f32_32x32x16_bf16 v[18:33], v[34:37], v[82:85], v[66:81]
	s_waitcnt lgkmcnt(10)
	v_mfma_f32_32x32x16_bf16 v[34:49], v[154:157], v[82:85], v[66:81]
	s_waitcnt lgkmcnt(9)
	v_mfma_f32_32x32x16_bf16 v[18:33], v[158:161], v[86:89], v[18:33]
	s_waitcnt lgkmcnt(8)
	v_mfma_f32_32x32x16_bf16 v[34:49], v[162:165], v[86:89], v[34:49]
	s_waitcnt lgkmcnt(7)
	v_mfma_f32_32x32x16_bf16 v[18:33], v[166:169], v[90:93], v[18:33]
	s_waitcnt lgkmcnt(6)
	v_mfma_f32_32x32x16_bf16 v[34:49], v[170:173], v[90:93], v[34:49]
	s_waitcnt lgkmcnt(5)
	v_mfma_f32_32x32x16_bf16 v[18:33], v[174:177], v[94:97], v[18:33]
	s_waitcnt lgkmcnt(4)
	v_mfma_f32_32x32x16_bf16 v[34:49], v[178:181], v[94:97], v[34:49]
	s_waitcnt lgkmcnt(3)
	v_mfma_f32_32x32x16_bf16 v[18:33], v[198:201], v[98:101], v[18:33]
	s_waitcnt lgkmcnt(2)
	v_mfma_f32_32x32x16_bf16 v[34:49], v[202:205], v[98:101], v[34:49]
	s_waitcnt lgkmcnt(1)
	v_mfma_f32_32x32x16_bf16 v[18:33], v[206:209], v[102:105], v[18:33]
	s_waitcnt lgkmcnt(0)
	v_mfma_f32_32x32x16_bf16 v[34:49], v[210:213], v[102:105], v[34:49]
	s_nop 15
	s_nop 7

; #define AT_LAS __attribute__((address_space(3)))
; __device__ __forceinline__ s16x4 vtr(AT_LAS const char* p) { return __builtin_bit_cast(s16x4, __builtin_amdgcn_ds_read_tr16_b64_v4i16((AT_LAS v4i16_t*)p)); }
; __device__ __forceinline__ void pv(f32x16 (&o)[2], AT_LAS const char* vp, const u32x4& pw0, const u32x4& pw1, const u32x4& pw2, const u32x4& pw3) {
; #pragma unroll
;     for (int d0 = 0; d0 < 2; ++d0) { s16x4 lo[4], hh[4];
; #pragma unroll
;         for (int ks = 0; ks < 4; ++ks) { lo[ks] = vtr(vp + d0 * 4096 + ks * 1024); hh[ks] = vtr(vp + d0 * 4096 + ks * 1024 + 512); }
;     ...
;         o[d0] = __builtin_amdgcn_mfma_f32_32x32x16_bf16(__builtin_bit_cast(bf16x8, pw0), AT_VF(0), o[d0], 0, 0, 0);
;         o[d0] = __builtin_amdgcn_mfma_f32_32x32x16_bf16(__builtin_bit_cast(bf16x8, pw1), AT_VF(1), o[d0], 0, 0, 0);
;         o[d0] = __builtin_amdgcn_mfma_f32_32x32x16_bf16(__builtin_bit_cast(bf16x8, pw2), AT_VF(2), o[d0], 0, 0, 0);
;         o[d0] = __builtin_amdgcn_mfma_f32_32x32x16_bf16(__builtin_bit_cast(bf16x8, pw3), AT_VF(3), o[d0], 0, 0, 0);
;     ...
;     }
; }
; __device__ __forceinline__ void qkt(f32x16& p0, f32x16& p1, AT_LAS const char* kb, const bf16x8 (&qr)[6], const f32x16& negm) {
;     bf16x8 kf[12];
; #pragma unroll
;     for (int d0 = 0; d0 < 6; ++d0) { kf[2 * d0] = *(AT_LAS const bf16x8*)(kb + d0 * 2048); kf[2 * d0 + 1] = *(AT_LAS const bf16x8*)(kb + d0 * 2048 + 512); }
;     __builtin_amdgcn_sched_barrier(0);
;     p0 = __builtin_amdgcn_mfma_f32_32x32x16_bf16(kf[0], qr[0], negm, 0, 0, 0); p1 = __builtin_amdgcn_mfma_f32_32x32x16_bf16(kf[1], qr[0], negm, 0, 0, 0);
; #pragma unroll
;     for (int d0 = 1; d0 < 6; ++d0) { p0 = __builtin_amdgcn_mfma_f32_32x32x16_bf16(kf[2 * d0], qr[d0], p0, 0, 0, 0); p1 = __builtin_amdgcn_mfma_f32_32x32x16_bf16(kf[2 * d0 + 1], qr[d0], p1, 0, 0, 0); }
;     asm volatile("s_nop 15\n\ts_nop 7" : "+v"(p0), "+v"(p1));
; }
; template <int THRL>
; __device__ __forceinline__ void attn_item(int b, int h, int s, const bf16_t* Q, const bf16_t* KN, const bf16_t* KR, const bf16_t* V, const float* goa  , bf16_t* Y, float* ssqy, AT_LAS char* shm, int wid0) {
;     ...
;             if (late) { if (have) pv(o, vp0 + ((t - 1) & 3) * VSLOTB, pw0, pw1, pw2, pw3);
;                         have = false; if (need) qkt(p0, p1, kp0 + (t & 3) * KSLOTB, qr, negm); }
.LBB13_1746:
	s_and_b64 vcc, s[96:97], s[92:93]
	s_cbranch_vccz .Lat1_l_slow
	s_and_b32 s88, s9, 0x6000
	v_add_u32_e32 v214, s88, v191
	s_add_i32 s88, s80, -3
	s_and_b32 s88, s88, 3
	s_mulk_i32 s88, 0x3000
	v_add_u32_e32 v215, s88, v190
	ds_read_b64_tr_b16 v[216:217], v214 offset:49152
	ds_read_b64_tr_b16 v[218:219], v214 offset:49664
	ds_read_b64_tr_b16 v[220:221], v214 offset:50176
	ds_read_b64_tr_b16 v[222:223], v214 offset:50688
	ds_read_b64_tr_b16 v[224:225], v214 offset:51200
	ds_read_b64_tr_b16 v[226:227], v214 offset:51712
	ds_read_b64_tr_b16 v[228:229], v214 offset:52224
	ds_read_b64_tr_b16 v[230:231], v214 offset:52736
	ds_read_b64_tr_b16 v[232:233], v214 offset:53248
	ds_read_b64_tr_b16 v[234:235], v214 offset:53760
	ds_read_b64_tr_b16 v[240:241], v214 offset:54272
	ds_read_b64_tr_b16 v[242:243], v214 offset:54784
	ds_read_b64_tr_b16 v[244:245], v214 offset:55296
	ds_read_b64_tr_b16 v[246:247], v214 offset:55808
	ds_read_b64_tr_b16 v[248:249], v214 offset:56320
	s_waitcnt lgkmcnt(13)
	v_mfma_f32_32x32x16_bf16 v[50:65], v[110:113], v[216:219], v[50:65]
	ds_read_b64_tr_b16 v[250:251], v214 offset:56832
	v_add_u32_e32 v236, s88, v252
	ds_read_b128 v[34:37], v236
	s_waitcnt lgkmcnt(13)
	v_mfma_f32_32x32x16_bf16 v[50:65], v[106:109], v[220:223], v[50:65]
	ds_read_b128 v[154:157], v236 offset:4096
	v_add_u32_e32 v239, s88, v253
	ds_read_b128 v[158:161], v239
	s_waitcnt lgkmcnt(13)
	v_mfma_f32_32x32x16_bf16 v[50:65], v[118:121], v[224:227], v[50:65]
	ds_read_b128 v[162:165], v239 offset:4096
	v_add_u32_e32 v236, s88, v254
	ds_read_b128 v[166:169], v236
	s_waitcnt lgkmcnt(13)
	v_mfma_f32_32x32x16_bf16 v[50:65], v[114:117], v[228:231], v[50:65]
	ds_read_b128 v[170:173], v236 offset:4096
	v_add_u32_e32 v239, s88, v255
	ds_read_b128 v[174:177], v239
	s_waitcnt lgkmcnt(13)
	v_mfma_f32_32x32x16_bf16 v[2:17], v[110:113], v[232:235], v[2:17]
	ds_read_b128 v[178:181], v239 offset:4096
	ds_read_b128 v[198:201], v215 offset:8192
	s_waitcnt lgkmcnt(13)
	v_mfma_f32_32x32x16_bf16 v[2:17], v[106:109], v[240:243], v[2:17]
	ds_read_b128 v[202:205], v215 offset:8704
	ds_read_b128 v[206:209], v215 offset:10240
	s_waitcnt lgkmcnt(13)
	v_mfma_f32_32x32x16_bf16 v[2:17], v[118:121], v[244:247], v[2:17]
	ds_read_b128 v[210:213], v215 offset:10752
	s_waitcnt lgkmcnt(12)
	v_mfma_f32_32x32x16_bf16 v[2:17], v[114:117], v[248:251], v[2:17]
	s_waitcnt lgkmcnt(11)
	v_mfma_f32_32x32x16_bf16 v[18:33], v[34:37], v[82:85], v[66:81]
	s_waitcnt lgkmcnt(10)
	v_mfma_f32_32x32x16_bf16 v[34:49], v[154:157], v[82:85], v[66:81]
	s_waitcnt lgkmcnt(9)
	v_mfma_f32_32x32x16_bf16 v[18:33], v[158:161], v[86:89], v[18:33]
	s_waitcnt lgkmcnt(8)
	v_mfma_f32_32x32x16_bf16 v[34:49], v[162:165], v[86:89], v[34:49]
	s_waitcnt lgkmcnt(7)
	v_mfma_f32_32x32x16_bf16 v[18:33], v[166:169], v[90:93], v[18:33]
	s_waitcnt lgkmcnt(6)
	v_mfma_f32_32x32x16_bf16 v[34:49], v[170:173], v[90:93], v[34:49]
	s_waitcnt lgkmcnt(5)
	v_mfma_f32_32x32x16_bf16 v[18:33], v[174:177], v[94:97], v[18:33]
	s_waitcnt lgkmcnt(4)
	v_mfma_f32_32x32x16_bf16 v[34:49], v[178:181], v[94:97], v[34:49]
	s_waitcnt lgkmcnt(3)
	v_mfma_f32_32x32x16_bf16 v[18:33], v[198:201], v[98:101], v[18:33]
	s_waitcnt lgkmcnt(2)
	v_mfma_f32_32x32x16_bf16 v[34:49], v[202:205], v[98:101], v[34:49]
	s_waitcnt lgkmcnt(1)
	v_mfma_f32_32x32x16_bf16 v[18:33], v[206:209], v[102:105], v[18:33]
	s_waitcnt lgkmcnt(0)
	v_mfma_f32_32x32x16_bf16 v[34:49], v[210:213], v[102:105], v[34:49]
	s_mov_b64 s[96:97], 0
	s_nop 7
	s_nop 3
	s_branch .LBB13_1751

; #define AT_LAS __attribute__((address_space(3)))
; __device__ __forceinline__ void qkt(f32x16& p0, f32x16& p1, AT_LAS const char* kb, const bf16x8 (&qr)[6], const f32x16& negm) {
;     bf16x8 kf[12];
; #pragma unroll
;     for (int d0 = 0; d0 < 6; ++d0) { kf[2 * d0] = *(AT_LAS const bf16x8*)(kb + d0 * 2048); kf[2 * d0 + 1] = *(AT_LAS const bf16x8*)(kb + d0 * 2048 + 512); }
;     __builtin_amdgcn_sched_barrier(0);
;     p0 = __builtin_amdgcn_mfma_f32_32x32x16_bf16(kf[0], qr[0], negm, 0, 0, 0); p1 = __builtin_amdgcn_mfma_f32_32x32x16_bf16(kf[1], qr[0], negm, 0, 0, 0);
; #pragma unroll
;     for (int d0 = 1; d0 < 6; ++d0) { p0 = __builtin_amdgcn_mfma_f32_32x32x16_bf16(kf[2 * d0], qr[d0], p0, 0, 0, 0); p1 = __builtin_amdgcn_mfma_f32_32x32x16_bf16(kf[2 * d0 + 1], qr[d0], p1, 0, 0, 0); }
;     asm volatile("s_nop 15\n\ts_nop 7" : "+v"(p0), "+v"(p1));
; }
; template <int THRL>
; __device__ __forceinline__ void attn_item(int b, int h, int s, const bf16_t* Q, const bf16_t* KN, const bf16_t* KR, const bf16_t* V, const float* goa  , bf16_t* Y, float* ssqy, AT_LAS char* shm, int wid0) {
;     ...
;                         have = false; if (need) qkt(p0, p1, kp0 + (t & 3) * KSLOTB, qr, negm); }
.LBB13_1748:
	s_andn2_b64 vcc, exec, s[92:93]
	s_cbranch_vccnz .LBB13_1750
	s_add_i32 s88, s80, -3
	s_and_b32 s88, s88, 3
	s_mulk_i32 s88, 0x3000
	v_add_u32_e32 v0, s88, v190
	v_add_u32_e32 v236, s88, v252
	ds_read_b128 v[34:37], v236
	ds_read_b128 v[154:157], v236 offset:4096
	v_add_u32_e32 v239, s88, v253
	ds_read_b128 v[158:161], v239
	ds_read_b128 v[162:165], v239 offset:4096
	v_add_u32_e32 v236, s88, v254
	ds_read_b128 v[166:169], v236
	ds_read_b128 v[170:173], v236 offset:4096
	v_add_u32_e32 v239, s88, v255
	ds_read_b128 v[174:177], v239
	ds_read_b128 v[178:181], v239 offset:4096
	ds_read_b128 v[198:201], v0 offset:8192
	ds_read_b128 v[202:205], v0 offset:8704
	ds_read_b128 v[206:209], v0 offset:10240
	ds_read_b128 v[210:213], v0 offset:10752
	s_waitcnt lgkmcnt(11)
	v_mfma_f32_32x32x16_bf16 v[18:33], v[34:37], v[82:85], v[66:81]
	s_waitcnt lgkmcnt(10)
	v_mfma_f32_32x32x16_bf16 v[34:49], v[154:157], v[82:85], v[66:81]
	s_waitcnt lgkmcnt(9)
	v_mfma_f32_32x32x16_bf16 v[18:33], v[158:161], v[86:89], v[18:33]
	s_waitcnt lgkmcnt(8)
	v_mfma_f32_32x32x16_bf16 v[34:49], v[162:165], v[86:89], v[34:49]
	s_waitcnt lgkmcnt(7)
	v_mfma_f32_32x32x16_bf16 v[18:33], v[166:169], v[90:93], v[18:33]
	s_waitcnt lgkmcnt(6)
	v_mfma_f32_32x32x16_bf16 v[34:49], v[170:173], v[90:93], v[34:49]
	s_waitcnt lgkmcnt(5)
	v_mfma_f32_32x32x16_bf16 v[18:33], v[174:177], v[94:97], v[18:33]
	s_waitcnt lgkmcnt(4)
	v_mfma_f32_32x32x16_bf16 v[34:49], v[178:181], v[94:97], v[34:49]
	s_waitcnt lgkmcnt(3)
	v_mfma_f32_32x32x16_bf16 v[18:33], v[198:201], v[98:101], v[18:33]
	s_waitcnt lgkmcnt(2)
	v_mfma_f32_32x32x16_bf16 v[34:49], v[202:205], v[98:101], v[34:49]
	s_waitcnt lgkmcnt(1)
	v_mfma_f32_32x32x16_bf16 v[18:33], v[206:209], v[102:105], v[18:33]
	s_waitcnt lgkmcnt(0)
	v_mfma_f32_32x32x16_bf16 v[34:49], v[210:213], v[102:105], v[34:49]
	s_nop 15
	s_nop 7

; #define AT_LAS __attribute__((address_space(3)))
; __device__ __forceinline__ void qkt(f32x16& p0, f32x16& p1, AT_LAS const char* kb, const bf16x8 (&qr)[6], const f32x16& negm) {
;     bf16x8 kf[12];
; #pragma unroll
;     for (int d0 = 0; d0 < 6; ++d0) { kf[2 * d0] = *(AT_LAS const bf16x8*)(kb + d0 * 2048); kf[2 * d0 + 1] = *(AT_LAS const bf16x8*)(kb + d0 * 2048 + 512); }
;     __builtin_amdgcn_sched_barrier(0);
;     p0 = __builtin_amdgcn_mfma_f32_32x32x16_bf16(kf[0], qr[0], negm, 0, 0, 0); p1 = __builtin_amdgcn_mfma_f32_32x32x16_bf16(kf[1], qr[0], negm, 0, 0, 0);
; #pragma unroll
;     for (int d0 = 1; d0 < 6; ++d0) { p0 = __builtin_amdgcn_mfma_f32_32x32x16_bf16(kf[2 * d0], qr[d0], p0, 0, 0, 0); p1 = __builtin_amdgcn_mfma_f32_32x32x16_bf16(kf[2 * d0 + 1], qr[d0], p1, 0, 0, 0); }
;     asm volatile("s_nop 15\n\ts_nop 7" : "+v"(p0), "+v"(p1));
; }
; template <int THRL>
; __device__ __forceinline__ void attn_item(int b, int h, int s, const bf16_t* Q, const bf16_t* KN, const bf16_t* KR, const bf16_t* V, const float* goa  , bf16_t* Y, float* ssqy, AT_LAS char* shm, int wid0) {
;     ...
;             if (!late) { if (t + 1 < NT && (jb + 1) <= wq) qkt(p0, p1, kp0 + ((t + 1) & 3) * KSLOTB, qr, negm); }
.LBB13_1761:
	s_add_i32 s92, s80, -2
	s_cmp_lt_u32 s92, s3
	s_cselect_b64 vcc, -1, 0
	s_cmp_lt_i32 s84, s33
	s_cselect_b64 s[88:89], -1, 0
	s_and_b64 s[88:89], vcc, s[88:89]
	s_andn2_b64 vcc, exec, s[88:89]
	s_cbranch_vccnz .LBB13_1742
	s_and_b32 s84, s92, 3
	s_mulk_i32 s84, 0x3000
	v_add_u32_e32 v0, s84, v190
	v_add_u32_e32 v236, s84, v252
	ds_read_b128 v[34:37], v236
	ds_read_b128 v[154:157], v236 offset:4096
	v_add_u32_e32 v239, s84, v253
	ds_read_b128 v[158:161], v239
	ds_read_b128 v[162:165], v239 offset:4096
	v_add_u32_e32 v236, s84, v254
	ds_read_b128 v[166:169], v236
	ds_read_b128 v[170:173], v236 offset:4096
	v_add_u32_e32 v239, s84, v255
	ds_read_b128 v[174:177], v239
	ds_read_b128 v[178:181], v239 offset:4096
	ds_read_b128 v[198:201], v0 offset:8192
	ds_read_b128 v[202:205], v0 offset:8704
	ds_read_b128 v[206:209], v0 offset:10240
	ds_read_b128 v[210:213], v0 offset:10752
	s_waitcnt lgkmcnt(11)
	v_mfma_f32_32x32x16_bf16 v[18:33], v[34:37], v[82:85], v[66:81]
	s_waitcnt lgkmcnt(10)
	v_mfma_f32_32x32x16_bf16 v[34:49], v[154:157], v[82:85], v[66:81]
	s_waitcnt lgkmcnt(9)
	v_mfma_f32_32x32x16_bf16 v[18:33], v[158:161], v[86:89], v[18:33]
	s_waitcnt lgkmcnt(8)
	v_mfma_f32_32x32x16_bf16 v[34:49], v[162:165], v[86:89], v[34:49]
	s_waitcnt lgkmcnt(7)
	v_mfma_f32_32x32x16_bf16 v[18:33], v[166:169], v[90:93], v[18:33]
	s_waitcnt lgkmcnt(6)
	v_mfma_f32_32x32x16_bf16 v[34:49], v[170:173], v[90:93], v[34:49]
	s_waitcnt lgkmcnt(5)
	v_mfma_f32_32x32x16_bf16 v[18:33], v[174:177], v[94:97], v[18:33]
	s_waitcnt lgkmcnt(4)
	v_mfma_f32_32x32x16_bf16 v[34:49], v[178:181], v[94:97], v[34:49]
	s_waitcnt lgkmcnt(3)
	v_mfma_f32_32x32x16_bf16 v[18:33], v[198:201], v[98:101], v[18:33]
	s_waitcnt lgkmcnt(2)
	v_mfma_f32_32x32x16_bf16 v[34:49], v[202:205], v[98:101], v[34:49]
	s_waitcnt lgkmcnt(1)
	v_mfma_f32_32x32x16_bf16 v[18:33], v[206:209], v[102:105], v[18:33]
	s_waitcnt lgkmcnt(0)
	v_mfma_f32_32x32x16_bf16 v[34:49], v[210:213], v[102:105], v[34:49]
	s_branch .LBB13_1742

; __device__ __forceinline__ u32x4 pack8(const f32x4& a, const f32x4& b) { u32x4 w; w.x = cvt_pk_bf16(a[0], a[1]); w.y = cvt_pk_bf16(a[2], a[3]); w.z = cvt_pk_bf16(b[0], b[1]); w.w = cvt_pk_bf16(b[2], b[3]); return w; }
; __device__ __forceinline__ float hsq4(const f32x4& a) { return (a[0] * a[0] + a[1] * a[1]) + (a[2] * a[2] + a[3] * a[3]); }
; #define AT_LAS __attribute__((address_space(3)))
; __device__ __forceinline__ int crow(int r, int hi) { return (r & 3) + 8 * (r >> 2) + 4 * hi; }
; template <int THRL>
; __device__ __forceinline__ void attn_item(int b, int h, int s, const bf16_t* Q, const bf16_t* KN, const bf16_t* KR, const bf16_t* V, const float* goa  , bf16_t* Y, float* ssqy, AT_LAS char* shm, int wid0) {
;     ...
;         asm volatile("s_waitcnt vmcnt(0) lgkmcnt(0)\n\ts_barrier" ::: "memory");
;         if (ui < 3) {
;             const int qbn = (ui == 0) ? 7 - s : (ui == 1) ? 2 + s : 5 - s; const int NTn = 4 * qbn + 4;
;             AT_QLOAD(qr, qbn); AT_DMA(0, 0, NTn); AT_DMA(1, 1, NTn); AT_DMA(2, 1, NTn); }
;         { auto rr = __builtin_amdgcn_permlane32_swap(__float_as_uint(l_reg), __float_as_uint(l_reg), false, false); l_reg = __uint_as_float(rr[0]) + __uint_as_float(rr[1]); }
;         if (hi == 0) wsf[32 + r32] = __builtin_amdgcn_rcpf(l_reg);
;         asm volatile("s_waitcnt lgkmcnt(0)" ::: "memory");
;         AT_LAS char* stg = shm + LDS_OST + wid * (32 * OROW);
;         { const int row = lane >> 1, half = lane & 1; const size_t grow = rowbase + q0 + wid * 32 + row; float ss = 0.f;
; #pragma unroll
;           for (int d0 = 0; d0 < 2; ++d0) {
; #pragma unroll
;             for (int r = 0; r < 16; ++r) { const int orow = crow(r, hi); *(AT_LAS float*)(stg + orow * OROW + r32 * 4) = o[d0][r] * wsf[32 + orow]; }
;             asm volatile("s_waitcnt lgkmcnt(0)" ::: "memory");
;             const float* gp = goa + h * 64 + d0 * 32 + half * 16; bf16_t* yp = Y + grow * YLD + 512 + h * 64 + d0 * 32 + half * 16;
; #pragma unroll
;             for (int i = 0; i < 2; ++i) { const f32x4 a = *(AT_LAS const f32x4*)(stg + row * OROW + half * 64 + i * 32), c = *(AT_LAS const f32x4*)(stg + row * OROW + half * 64 + i * 32 + 16);
;                 ss += pg8::hsq4(a) + pg8::hsq4(c);
;                 *(u32x4*)(yp + i * 8) = pg8::pack8(a * *(const f32x4*)(gp + i * 8), c * *(const f32x4*)(gp + i * 8 + 4)); }
.LBB13_1765:
	s_waitcnt vmcnt(0) lgkmcnt(0)
	s_barrier
	global_load_dwordx4 v[216:219], v[142:143], off offset:2064
	global_load_dwordx4 v[220:223], v[142:143], off offset:2048
	global_load_dwordx4 v[224:227], v[142:143], off offset:2096
	global_load_dwordx4 v[228:231], v[142:143], off offset:2080
	global_load_dwordx4 v[232:235], v[142:143], off offset:2192
	global_load_dwordx4 v[240:243], v[142:143], off offset:2176
	global_load_dwordx4 v[244:247], v[142:143], off offset:2224
	global_load_dwordx4 v[248:251], v[142:143], off offset:2208
	s_cmp_eq_u32 s8, 3
	s_cbranch_scc1 .Lat1_lastu
	s_and_b64 s[76:77], s[82:83], exec
	v_readlane_b32 s3, v238, 57
	s_cselect_b32 s3, s3, s86
	s_and_b64 s[76:77], s[94:95], exec
	v_readlane_b32 s5, v238, 59
	s_cselect_b32 s3, s5, s3
	s_lshl_b32 s3, s3, 8
	v_readlane_b32 s5, v238, 60
	s_add_u32 s3, s5, s3
	v_readlane_b32 s5, v238, 61
	s_addc_u32 s5, s5, 0
	s_mulk_i32 s5, 0x600
	v_mad_u64_u32 v[18:19], s[76:77], s3, v189, v[138:139]
	v_add_u32_e32 v19, s5, v19
	global_load_dwordx4 v[82:85], v[18:19], off
	global_load_dwordx4 v[86:89], v[18:19], off offset:32
	global_load_dwordx4 v[90:93], v[18:19], off offset:64
	global_load_dwordx4 v[94:97], v[18:19], off offset:96
	global_load_dwordx4 v[98:101], v[18:19], off offset:128
	global_load_dwordx4 v[102:105], v[18:19], off offset:160
	s_mov_b32 s3, m0
	s_mov_b32 m0, s87
	s_nop 0
	global_load_lds_dwordx4 v[122:123], off
	s_mov_b32 m0, s3
	v_readlane_b32 s5, v238, 50
	s_mov_b32 s3, m0
	s_mov_b32 m0, s2
	s_nop 0
	global_load_lds_dwordx4 v[124:125], off
	s_mov_b32 m0, s3
	v_readlane_b32 s9, v238, 53
	s_mov_b32 s3, m0
	s_mov_b32 m0, s78
	s_nop 0
	global_load_lds_dwordx4 v[126:127], off
	s_mov_b32 m0, s3
	s_nop 0
	s_mov_b32 s3, m0
	s_mov_b32 m0, s5
	s_nop 0
	global_load_lds_dwordx4 v[128:129], off
	s_mov_b32 m0, s3
	v_readlane_b32 s5, v238, 51
	s_mov_b32 s3, m0
	s_mov_b32 m0, s5
	s_nop 0
	global_load_lds_dwordx4 v[130:131], off
	s_mov_b32 m0, s3
	v_readlane_b32 s5, v238, 56
	s_mov_b32 s3, m0
	s_mov_b32 m0, s5
	s_nop 0
	global_load_lds_dwordx4 v[132:133], off
	s_mov_b32 m0, s3
	s_nop 0
	s_mov_b32 s3, m0
	s_mov_b32 m0, s9
	s_nop 0
	global_load_lds_dwordx4 v[134:135], off
	s_mov_b32 m0, s3
	v_readlane_b32 s9, v238, 55
	s_mov_b32 s3, m0
	s_mov_b32 m0, s9
	s_nop 0
	global_load_lds_dwordx4 v[136:137], off
	s_mov_b32 m0, s3
	s_nop 0
	s_mov_b32 s3, m0
	s_mov_b32 m0, s5
	s_nop 0
	global_load_lds_dwordx4 v[132:133], off
	s_mov_b32 m0, s3
